# GEMM unit loops (P1,P3,P4,P5): first K-loop iteration peeled with C=0 on each accumulator's first MFMA, removing the 128 v_mov accumulator zeroing per 256x256 unit
# speedup vs baseline: 1.0023x; 1.0023x over previous
; #define LAS __attribute__((address_space(3)))
; __device__ __forceinline__ unsigned xb_ld(unsigned* p)              { return __hip_atomic_load(p, __ATOMIC_RELAXED, __HIP_MEMORY_SCOPE_AGENT); }
; __device__ __forceinline__ unsigned xb_add(unsigned* p, unsigned v) { return __hip_atomic_fetch_add(p, v, __ATOMIC_RELAXED, __HIP_MEMORY_SCOPE_AGENT); }
; __device__ __forceinline__ unsigned xb_xcc_id() { return (unsigned)__builtin_amdgcn_s_getreg((3 << 11) | 20) & 0xFu; }
; __device__ __forceinline__ XcdBarrier xcd_barrier_post(unsigned* bar, volatile LAS unsigned* st) {
;     XcdBarrier b; b.bar = bar; b.x = xb_xcc_id(); b.st = st;
;     if (threadIdx.x == 0) (void)xb_add(&bar[XB_XCNT(b.x)], 1u);
;     return b;
; }
; __device__ __forceinline__ void xcd_barrier_complete(unsigned* bar, unsigned x, unsigned& nloc, unsigned& nx) {
;     const unsigned G = gridDim.x * gridDim.y * gridDim.z;
;     unsigned sum, cnt, mine, sp = 0u;
;     for (;;) {
;         sum = 0u; cnt = 0u; mine = 0u;
; #pragma unroll
;         for (unsigned j = 0; j < 16; ++j) { const unsigned c = xb_ld(&bar[XB_XCNT(j)]); sum += c; cnt += (c > 0u) ? 1u : 0u; mine = (j == x) ? c : mine; }
;         if (sum == G) break;
;         __builtin_amdgcn_s_sleep(1);
;         if ((++sp & 255u) == 0u) { if (xb_ld(&bar[XB_TMO])) break; if (sp > XB_SPIN_CAP) { atomicAdd(&bar[XB_TMO], 1u); break; } }
;     }
;     nloc = mine > 0u ? mine : 1u; nx = cnt > 0u ? cnt : 1u;
; }
.LBB0_123:
	s_or_b64 exec, exec, s[6:7]
	s_add_u32 s16, s24, 0x8200000
	s_addc_u32 s17, s25, 0
	s_add_u32 s4, s24, 0x1200
	s_addc_u32 s5, s25, 0
	v_writelane_b32 v252, s4, 57
	v_mbcnt_hi_u32_b32 v215, -1, v46
	v_and_b32_e32 v0, 64, v215
	v_writelane_b32 v252, s5, 58
	s_add_u32 s4, s24, 0x1400
	s_addc_u32 s5, s25, 0
	v_writelane_b32 v252, s4, 59
	s_waitcnt lgkmcnt(0)
	v_mov_b32_e32 v1, 0
	v_mov_b32_e32 v213, 1
	v_writelane_b32 v252, s5, 60
	s_add_u32 s4, s24, 0x1500
	s_addc_u32 s5, s25, 0
	v_writelane_b32 v252, s4, 61
	v_mov_b32_e32 v214, 0x358637bd
	v_mov_b32_e32 v192, 1.0
	v_writelane_b32 v252, s5, 62
	s_add_u32 s4, s24, 0x1600
	s_addc_u32 s5, s25, 0
	v_writelane_b32 v252, s4, 63
	v_xor_b32_e32 v216, 1, v215
	v_add_u32_e32 v217, 64, v0
	v_writelane_b32 v253, s5, 0
	s_add_u32 s4, s24, 0x1700
	s_addc_u32 s5, s25, 0
	v_writelane_b32 v253, s4, 1
	v_mov_b32_e32 v218, 0x3e38aa3b
	v_mov_b32_e32 v219, 0x1400
	v_writelane_b32 v253, s5, 2
	s_add_u32 s4, s24, 0x1800
	s_addc_u32 s5, s25, 0
	v_writelane_b32 v253, s4, 3
	v_mov_b32_e32 v220, 0x7c
	v_mov_b64_e32 v[194:195], 0x200
	v_writelane_b32 v253, s5, 4
	s_add_u32 s4, s24, 0x1900
	s_addc_u32 s5, s25, 0
	v_writelane_b32 v253, s4, 5
	v_mov_b64_e32 v[196:197], 0x1ff
	s_movk_i32 s76, 0x2000
	v_writelane_b32 v253, s5, 6
	s_add_u32 s4, s24, 0x1a00
	s_addc_u32 s5, s25, 0
	v_writelane_b32 v253, s4, 7
	s_mov_b32 s78, 0x40000
	s_mov_b32 s79, 0x42000
	v_writelane_b32 v253, s5, 8
	s_add_u32 s4, s24, 0x1b00
	s_addc_u32 s5, s25, 0
	v_writelane_b32 v253, s4, 9
	s_nop 1
	v_writelane_b32 v253, s5, 10
	s_add_u32 s4, s24, 0x1c00
	s_addc_u32 s5, s25, 0
	v_writelane_b32 v253, s4, 11
	s_nop 1
	v_writelane_b32 v253, s5, 12
	s_add_u32 s4, s24, 0x1d00
	s_addc_u32 s5, s25, 0
	v_writelane_b32 v253, s4, 13
	s_nop 1
	v_writelane_b32 v253, s5, 14
	s_add_u32 s4, s24, 0x1e00
	s_addc_u32 s5, s25, 0
	v_writelane_b32 v253, s4, 15
	s_nop 1
	v_writelane_b32 v253, s5, 16
	s_add_u32 s4, s24, 0x1f00
	s_addc_u32 s5, s25, 0
	v_writelane_b32 v253, s4, 17
	s_nop 1
	v_writelane_b32 v253, s5, 18
	s_add_u32 s4, s24, 0x2000
	s_addc_u32 s5, s25, 0
	v_writelane_b32 v253, s4, 19
	s_nop 1
	v_writelane_b32 v253, s5, 20
	s_add_u32 s4, s24, 0x2100
	s_addc_u32 s5, s25, 0
	v_writelane_b32 v253, s4, 21
	s_nop 1
	v_writelane_b32 v253, s5, 22
	s_add_u32 s4, s24, 0x2200
	s_addc_u32 s5, s25, 0
	v_writelane_b32 v253, s4, 23
	s_nop 1
	v_writelane_b32 v253, s5, 24
	s_add_u32 s4, s24, 0x2300
	s_addc_u32 s5, s25, 0
	v_writelane_b32 v253, s4, 25
	s_cmp_eq_u32 s3, 15
	s_nop 0
	v_writelane_b32 v253, s5, 26
	s_cselect_b64 s[4:5], -1, 0
	v_writelane_b32 v253, s4, 27
	s_cmp_eq_u32 s3, 14
	s_nop 0
	v_writelane_b32 v253, s5, 28
	s_cselect_b64 s[4:5], -1, 0
	v_writelane_b32 v253, s4, 29
	s_cmp_eq_u32 s3, 13
	s_nop 0
	v_writelane_b32 v253, s5, 30
	s_cselect_b64 s[4:5], -1, 0
	v_writelane_b32 v253, s4, 31
	s_cmp_eq_u32 s3, 12
	s_nop 0
	v_writelane_b32 v253, s5, 32
	s_cselect_b64 s[4:5], -1, 0
	v_writelane_b32 v253, s4, 33
	s_cmp_eq_u32 s3, 11
	s_nop 0
	v_writelane_b32 v253, s5, 34
	s_cselect_b64 s[4:5], -1, 0
	v_writelane_b32 v253, s4, 35
	s_cmp_eq_u32 s3, 10
	s_nop 0
	v_writelane_b32 v253, s5, 36
	s_cselect_b64 s[4:5], -1, 0
	v_writelane_b32 v253, s4, 37
	s_cmp_eq_u32 s3, 9
	s_nop 0
	v_writelane_b32 v253, s5, 38
	s_cselect_b64 s[4:5], -1, 0
	v_writelane_b32 v253, s4, 39
	s_cmp_eq_u32 s3, 8
	s_nop 0
	v_writelane_b32 v253, s5, 40
	s_cselect_b64 s[4:5], -1, 0
	v_writelane_b32 v253, s4, 41
	s_cmp_eq_u32 s3, 7
	s_nop 0
	v_writelane_b32 v253, s5, 42
	s_cselect_b64 s[4:5], -1, 0
	v_writelane_b32 v253, s4, 43
	s_cmp_eq_u32 s3, 6
	s_nop 0
	v_writelane_b32 v253, s5, 44
	s_cselect_b64 s[4:5], -1, 0
	v_writelane_b32 v253, s4, 45
	s_cmp_eq_u32 s3, 5
	s_nop 0
	v_writelane_b32 v253, s5, 46
	s_cselect_b64 s[4:5], -1, 0
	v_writelane_b32 v253, s4, 47
	s_cmp_eq_u32 s3, 4
	s_nop 0
	v_writelane_b32 v253, s5, 48
	s_cselect_b64 s[4:5], -1, 0
	v_writelane_b32 v253, s4, 49
	s_cmp_eq_u32 s3, 3
	s_nop 0
	v_writelane_b32 v253, s5, 50
	s_cselect_b64 s[4:5], -1, 0
	v_writelane_b32 v253, s4, 51
	s_cmp_eq_u32 s3, 2
	s_nop 0
	v_writelane_b32 v253, s5, 52
	s_cselect_b64 s[4:5], -1, 0
	v_writelane_b32 v253, s4, 53
	s_cmp_eq_u32 s3, 1
	s_nop 0
	v_writelane_b32 v253, s5, 54
	s_cselect_b64 s[4:5], -1, 0
	v_writelane_b32 v253, s4, 55
	s_cmp_eq_u32 s3, 0
	s_nop 0
	v_writelane_b32 v253, s5, 56
	s_cselect_b64 s[4:5], -1, 0
	s_lshl_b32 s3, s3, 8
	s_add_u32 s0, s0, s3
	v_writelane_b32 v253, s4, 57
	s_addc_u32 s1, s1, 0
	s_nop 0
	v_writelane_b32 v253, s5, 58
	s_add_u32 s4, s0, 0x1400
	s_addc_u32 s5, s1, 0
	v_writelane_b32 v253, s4, 59
	s_add_u32 s0, s0, 0x2400
	s_addc_u32 s1, s1, 0
	v_writelane_b32 v253, s5, 60
	v_writelane_b32 v253, s0, 61
	v_readlane_b32 s4, v252, 0
	s_nop 0
	v_writelane_b32 v253, s1, 62
	s_add_u32 s0, s24, 0x4400
	s_addc_u32 s1, s25, 0
	v_writelane_b32 v253, s0, 63
	s_nop 1
	v_writelane_b32 v254, s1, 0
	s_add_u32 s0, s24, 0x4500
	s_addc_u32 s1, s25, 0
	v_writelane_b32 v254, s0, 1
	s_nop 1
	v_writelane_b32 v254, s1, 2
	s_add_u32 s0, s24, 0x200000
	v_writelane_b32 v254, s0, 3
	s_addc_u32 s0, s25, 0
	s_cmpk_lt_i32 s4, 0x500
	v_writelane_b32 v254, s0, 4
	s_cselect_b64 s[0:1], -1, 0
	v_writelane_b32 v254, s0, 5
	s_ashr_i32 s3, s26, 31
	s_nop 0
	v_writelane_b32 v254, s1, 6
	s_ashr_i32 s0, s4, 31
	v_writelane_b32 v254, s0, 7
	s_lshr_b32 s0, s0, 29
	s_add_i32 s0, s4, s0
	s_ashr_i32 s1, s0, 3
	s_and_b32 s0, s0, -8
	s_sub_i32 s0, s4, s0
	s_cmp_lt_i32 s4, 40
	s_cselect_b64 s[6:7], -1, 0
	s_add_u32 s12, s24, 0x12400000
	s_addc_u32 s13, s25, 0
;     __host__ __device__ bool next(int i, Unit& u) const {
;         const long L = (long)i * G + c; if (L >= nwg) return false;
;         int wgid = (int)L; { const int q = nwg / NXCD, r = nwg % NXCD, xcd = wgid % NXCD, off = wgid / NXCD; wgid = (xcd < r ? xcd * (q + 1) : r * (q + 1) + (xcd - r) * q) + off; }
;         const int nig = WGM * nN, gid = wgid / nig, fm = gid * WGM, gsz = (nM - fm) < WGM ? (nM - fm) : WGM;
;         u.pm = fm + ((wgid % nig) % gsz); u.pn = (wgid % nig) / gsz; return true;
;     }
; __global__ void __launch_bounds__(512) hymba_fwd(Params p) {
;     ...
;     for (int l = 0; l < 2; ++l) {
;         xcd_barrier(xbar);
;         unsigned char* wl = ws + WS_W + (size_t)l * W_LAYER;
	v_writelane_b32 v254, s3, 8
	s_add_u32 s22, s24, 0x14500000
	v_writelane_b32 v254, s6, 9
	s_addc_u32 s23, s25, 0
	s_nop 0
	v_writelane_b32 v254, s7, 10
	s_add_u32 s6, s24, 0x3700000
	s_addc_u32 s7, s25, 0
	v_writelane_b32 v254, s6, 11
	s_nop 1
	v_writelane_b32 v254, s7, 12
	s_add_u32 s6, s24, 0x3900000
	s_addc_u32 s7, s25, 0
	v_writelane_b32 v254, s6, 13
	s_cmpk_lt_i32 s4, 0x204
	s_nop 0
	v_writelane_b32 v254, s7, 14
	s_cselect_b64 s[6:7], -1, 0
	v_writelane_b32 v254, s6, 15
	s_cmpk_lt_i32 s4, 0x200
	s_nop 0
	v_writelane_b32 v254, s7, 16
	s_cselect_b64 s[6:7], -1, 0
	s_lshl_b32 s3, s0, 6
	v_writelane_b32 v254, s6, 17
	s_cmp_lt_i32 s4, 16
	s_nop 0
	v_writelane_b32 v254, s7, 18
	s_cselect_b64 s[6:7], -1, 0
	v_writelane_b32 v254, s6, 19
	s_cmpk_lt_i32 s4, 0xb00
	s_nop 0
	v_writelane_b32 v254, s7, 20
	s_cselect_b64 s[6:7], -1, 0
	v_writelane_b32 v254, s6, 21
	s_cmpk_lt_i32 s4, 0x58
	s_cselect_b64 s[4:5], -1, 0
	v_writelane_b32 v254, s7, 22
	v_writelane_b32 v254, s4, 23
	s_cmp_lt_i32 s0, 0
	s_nop 0
	v_writelane_b32 v254, s5, 24
	s_mul_i32 s4, s0, 0x41
	s_cselect_b32 s3, s4, s3
	s_movk_i32 s4, 0xa1
	s_cselect_b32 s4, s4, 0xa0
	s_mul_i32 s4, s0, s4
	s_movk_i32 s5, 0x161
	s_cselect_b32 s5, s5, 0x160
	s_add_i32 s4, s4, s1
	s_mul_hi_i32 s6, s4, 0x66666667
	s_lshr_b32 s7, s6, 31
	s_ashr_i32 s6, s6, 4
	s_add_i32 s6, s6, s7
	s_mul_i32 s7, s6, 40
	s_sub_i32 s4, s4, s7
	s_bfe_i32 s7, s4, 0x80000
	s_bfe_u32 s7, s7, 0x2000d
	s_add_i32 s7, s4, s7
	s_and_b32 s8, s7, 0xfc
	s_add_i32 s3, s3, s1
	s_mul_i32 s0, s0, s5
	s_sub_i32 s4, s4, s8
	s_ashr_i32 s8, s3, 31
	s_add_i32 s0, s0, s1
	s_lshr_b32 s8, s8, 28
	s_mul_hi_i32 s1, s0, 0x2e8ba2e9
	s_add_i32 s8, s3, s8
	s_lshr_b32 s5, s1, 31
	s_ashr_i32 s1, s1, 4
	s_and_b32 s9, s8, 0xfff0
	s_add_i32 s1, s1, s5
	s_sub_i32 s3, s3, s9
	s_mul_i32 s5, s1, 0x58
	s_bfe_i32 s9, s3, 0x80000
	s_sub_i32 s0, s0, s5
	s_bfe_u32 s9, s9, 0x2000d
	s_bfe_i32 s5, s0, 0x80000
	s_add_i32 s9, s3, s9
	s_bfe_u32 s5, s5, 0x2000d
	s_and_b32 s10, s9, 0xfc
	s_add_i32 s5, s0, s5
	s_sub_i32 s3, s3, s10
	s_and_b32 s10, s5, 0xfc
	s_lshl_b32 s6, s6, 2
	s_sext_i32_i8 s4, s4
	s_sub_i32 s0, s0, s10
	s_bfe_i32 s7, s7, 0x80000
	s_add_i32 s10, s6, s4
	s_ashr_i32 s4, s8, 4
	s_sext_i32_i16 s7, s7
	s_lshl_b32 s4, s4, 2
	s_bfe_i32 s6, s9, 0x80000
	s_sext_i32_i8 s3, s3
	s_lshl_b32 s1, s1, 2
	s_sext_i32_i8 s0, s0
	s_sext_i32_i16 s6, s6
	s_add_i32 s14, s4, s3
	s_bfe_i32 s3, s5, 0x80000
	s_add_i32 s20, s1, s0
	s_ashr_i32 s0, s7, 2
	s_sext_i32_i16 s3, s3
	s_ashr_i32 s21, s20, 31
	v_writelane_b32 v254, s0, 25
	s_ashr_i32 s1, s6, 2
	s_lshr_b32 s0, s7, 2
	v_writelane_b32 v254, s1, 26
	s_lshr_b32 s4, s6, 2
	s_ashr_i32 s1, s3, 2
	s_lshr_b32 s6, s3, 2
	s_lshl_b64 s[8:9], s[20:21], 19
	s_add_u32 s8, s18, s8
	s_addc_u32 s9, s19, s9
	s_bfe_i64 s[6:7], s[6:7], 0x100000
	v_writelane_b32 v254, s1, 27
	s_lshl_b64 s[6:7], s[6:7], 19
	v_writelane_b32 v254, s6, 28
	s_lshl_b32 s1, s20, 8
	s_nop 0
	v_writelane_b32 v254, s7, 29
	s_mov_b32 s6, s20
	v_writelane_b32 v254, s6, 30
	s_nop 1
	v_writelane_b32 v254, s7, 31
	v_writelane_b32 v254, s1, 32
	s_add_u32 s6, s8, 0x40000
	v_writelane_b32 v254, s8, 33
	s_addc_u32 s7, s9, 0
	s_ashr_i32 s11, s10, 31
	v_writelane_b32 v254, s9, 34
	v_writelane_b32 v254, s6, 35
	s_mov_b64 s[8:9], 0
	s_nop 0
	v_writelane_b32 v254, s7, 36
	s_lshl_b64 s[6:7], s[10:11], 19
	s_add_u32 s6, s18, s6
	s_addc_u32 s7, s19, s7
	s_bfe_i64 s[0:1], s[0:1], 0x100000
	s_lshl_b64 s[0:1], s[0:1], 19
	v_writelane_b32 v254, s0, 37
	s_nop 1
	v_writelane_b32 v254, s1, 38
	s_mov_b32 s0, s10
	v_writelane_b32 v254, s0, 39
	s_nop 1
	v_writelane_b32 v254, s1, 40
	s_lshl_b32 s0, s10, 8
	v_writelane_b32 v254, s0, 41
	s_add_u32 s0, s6, 0x40000
	v_writelane_b32 v254, s6, 42
	s_addc_u32 s1, s7, 0
	s_ashr_i32 s15, s14, 31
	v_writelane_b32 v254, s7, 43
	v_writelane_b32 v254, s0, 44
	s_mov_b32 s7, 0
	s_mov_b32 s44, s7
	v_writelane_b32 v254, s1, 45
	s_bfe_i64 s[0:1], s[4:5], 0x100000
	s_lshl_b64 s[0:1], s[0:1], 19
	v_writelane_b32 v254, s0, 46
	v_readlane_b32 s4, v252, 51
	v_readlane_b32 s5, v252, 52
	v_writelane_b32 v254, s1, 47
	s_lshl_b64 s[0:1], s[14:15], 19
	s_add_u32 s4, s4, s0
	s_addc_u32 s5, s5, s1
	s_mul_i32 s0, s27, s26
	s_mul_i32 s6, s0, s2
	s_add_u32 s0, s4, 0x40000
	v_writelane_b32 v254, s4, 48
	s_addc_u32 s1, s5, 0
	s_mov_b32 s2, s14
	v_writelane_b32 v254, s5, 49
	v_writelane_b32 v254, s0, 50
	s_mov_b64 s[4:5], -1
	s_nop 0
	v_writelane_b32 v254, s1, 51
	v_writelane_b32 v254, s2, 52
	s_mul_i32 s1, s14, 0x160000
	s_mul_hi_i32 s0, s14, 0x160000
	v_writelane_b32 v254, s3, 53
	s_add_u32 s2, s16, s1
	s_addc_u32 s3, s17, s0
	s_add_u32 s0, s2, 0xb0000
	v_writelane_b32 v254, s2, 54
	s_addc_u32 s1, s3, 0
	s_nop 0
	v_writelane_b32 v254, s3, 55
	v_writelane_b32 v254, s0, 56
	s_nop 1
	v_writelane_b32 v254, s1, 57
	s_add_u32 s0, s24, 0x390f800
	s_addc_u32 s1, s25, 0
	v_writelane_b32 v254, s0, 58
	s_nop 1
	v_writelane_b32 v254, s1, 59
	s_add_u32 s0, s24, 0x3903800
	s_addc_u32 s1, s25, 0
	v_writelane_b32 v254, s0, 60
	s_nop 1
	v_writelane_b32 v254, s1, 61
	s_add_i32 s0, 0, 0x22040
	v_writelane_b32 v254, s0, 62
	s_add_i32 s0, 0, 0x22044
	v_writelane_b32 v254, s0, 63
	s_add_i32 s0, 0, 0x22000
	v_writelane_b32 v255, s0, 0
	s_mov_b64 s[0:1], 0x80
	v_writelane_b32 v255, s6, 1
	s_branch .LBB0_125
.Lkernel_end_near:
	s_endpgm
.LBB0_124:
	v_readlane_b32 s2, v255, 2
	v_readlane_b32 s3, v255, 3
	s_mov_b32 s44, 1
	s_mov_b64 s[8:9], -1
	s_mov_b64 s[4:5], 0
	s_and_b64 vcc, exec, s[2:3]
	v_readlane_b32 s6, v255, 1
	s_cbranch_vccnz .Lkernel_end_near

; #define PG8_STAGE(bufoff, gbase, voff) do { _Pragma("unroll") for (int _i = 0; _i < 2; ++_i) \
;         __builtin_amdgcn_global_load_lds((const unsigned*)((const char*)(gbase) + (voff)[_i]), (PG8_LAS unsigned*)(lds + (bufoff) + ldsw + _i * 8192), 16, 0, 0); } while (0)
; #define PG8_LDA(dst, b, h) do { _Pragma("unroll") for (int m = 0; m < 4; ++m) _Pragma("unroll") for (int k = 0; k < 2; ++k) dst[m][k] = *(const PG8_LAS bf16x8*)(lds + PG8_SA(b, h) + aoff + m * 2048 + k * 1024); } while (0)
; #define PG8_LDB(dst, b, h) do { _Pragma("unroll") for (int n = 0; n < 2; ++n) _Pragma("unroll") for (int k = 0; k < 2; ++k) dst[n][k] = *(const PG8_LAS bf16x8*)(lds + PG8_SB(b, h) + boff + n * 2048 + k * 1024); } while (0)
; #define PG8_MMA(ai, bj, At, Bt) do { __builtin_amdgcn_s_setprio(1); _Pragma("unroll") for (int m = 0; m < 4; ++m) _Pragma("unroll") for (int n = 0; n < 2; ++n) _Pragma("unroll") for (int k = 0; k < 2; ++k) \
;         acc[ai][bj][m][n] = __builtin_amdgcn_mfma_f32_16x16x32_bf16(Bt[n][k], At[m][k], acc[ai][bj][m][n], 0, 0, 0); __builtin_amdgcn_s_setprio(0); } while (0)
; #define PG8_BAR __builtin_amdgcn_s_barrier()
; template <class Epi, class Sched, bool ALIGN_EPI = false, bool SP2 = false>
; __device__ __forceinline__ void gemm_phase(PG8_LAS unsigned char* lds, const Gemm g, const Sched& S, const Epi& E) {
;     ...
;         const bool has_next = S.next(ui + 1, nxt);
;         const char* nA = has_next ? (const char*)g.A + (size_t)nxt.pm * tstep : cA; const char* nB = has_next ? (const char*)g.Bt + (size_t)nxt.pn * tstep : cB;
;         for (int t = 0; t < nt; t += 2) {
;             const bool last = (t == nt - 2);
;             const char* a1 = cA + (size_t)(t + 1) * kstep;
;             const char* a2 = last ? nA : cA + (size_t)(t + 2) * kstep; const char* b2 = last ? nB : cB + (size_t)(t + 2) * kstep;
;             const char* a3 = a2 + kstep; const char* b3 = b2 + kstep;
;             if (last && has_next) S.a_ready(nxt);
;             if constexpr (SP2) {
;             PG8_LDB(B0, 0, 0); PG8_LDB(B1, 0, 1); PG8_SCHED; PG8_LDA(At, 0, 0); PG8_STAGE(PG8_SA(1, 1), a1 + hstep, voffA);
;             PG8_WAIT_V(8); PG8_WAIT_L(0); PG8_BAR; PG8_MMA(0, 0, At, B0); PG8_MMA(0, 1, At, B1); PG8_BAR; PG8_SCHED;
;             PG8_LDA(At, 0, 1); PG8_STAGE(PG8_SB(0, 0), b2, voffB); PG8_STAGE(PG8_SB(0, 1), b2 + hstep, voffB); PG8_STAGE(PG8_SA(0, 0), a2, voffA);
.LBB0_187:
	s_ashr_i32 s53, s52, 31
	s_lshl_b64 s[14:15], s[52:53], 19
	s_add_u32 s54, s18, s14
	s_addc_u32 s55, s19, s15
	s_and_b64 s[14:15], s[38:39], exec
	s_cselect_b32 s33, s55, s9
	s_cselect_b32 s34, s54, s8
	s_ashr_i32 s51, s50, 31
	s_lshl_b64 s[14:15], s[50:51], 19
	v_readlane_b32 s30, v255, 4
	s_add_u32 s56, s30, s14
	v_readlane_b32 s14, v255, 5
	s_addc_u32 s57, s14, s15
	s_and_b64 s[14:15], s[38:39], exec
	s_cselect_b32 s35, s57, s11
	s_cselect_b32 s40, s56, s10
	s_add_u32 s8, s8, 0x40080
	s_addc_u32 s9, s9, 0
	s_add_u32 s41, s10, 0x100
	s_addc_u32 s42, s11, 0
	s_mov_b32 s43, -2
.Lpeel_p1:
	s_add_u32 s10, s8, 0xfffc0080
	s_addc_u32 s11, s9, -1
	s_add_i32 s30, 0, 0x10000
	s_cmp_eq_u32 s43, 12
	s_cselect_b32 s15, s33, s11
	s_cselect_b32 s14, s34, s10
	v_add_u32_e32 v0, s30, v204
	s_cselect_b32 s11, s35, s42
	s_cselect_b32 s10, s40, s41
	s_add_i32 s51, 0, 0x14000
	ds_read_b128 v[18:21], v0
	ds_read_b128 v[22:25], v0 offset:1024
	ds_read_b128 v[26:29], v0 offset:2048
	ds_read_b128 v[30:33], v0 offset:3072
	v_add_u32_e32 v0, s51, v204
	ds_read_b128 v[46:49], v0
	ds_read_b128 v[54:57], v0 offset:1024
	ds_read_b128 v[170:173], v0 offset:2048
	ds_read_b128 v[174:177], v0 offset:3072
	v_lshl_add_u64 v[190:191], s[8:9], 0, v[166:167]
	s_add_i32 m0, s21, 0xc000
	ds_read_b128 v[178:181], v225
	ds_read_b128 v[182:185], v225 offset:1024
	ds_read_b128 v[186:189], v225 offset:2048
	ds_read_b128 v[226:229], v225 offset:3072
	ds_read_b128 v[230:233], v225 offset:4096
	ds_read_b128 v[234:237], v225 offset:5120
	ds_read_b128 v[238:241], v225 offset:6144
	ds_read_b128 v[242:245], v225 offset:7168
	global_load_lds_dwordx4 v[190:191], off
	v_lshl_add_u64 v[190:191], s[8:9], 0, v[168:169]
	s_add_i32 m0, s21, 0xe000
	s_nop 0
	global_load_lds_dwordx4 v[190:191], off
	s_waitcnt vmcnt(8)
	s_waitcnt lgkmcnt(0)
	s_barrier
	s_setprio 1
	s_waitcnt lgkmcnt(0)
	v_mfma_f32_16x16x32_bf16 v[150:153], v[18:21], v[178:181], 0
	v_mfma_f32_16x16x32_bf16 v[146:149], v[26:29], v[178:181], 0
	v_mfma_f32_16x16x32_bf16 v[134:137], v[18:21], v[186:189], 0
	v_mfma_f32_16x16x32_bf16 v[130:133], v[26:29], v[186:189], 0
	v_mfma_f32_16x16x32_bf16 v[118:121], v[18:21], v[230:233], 0
	v_mfma_f32_16x16x32_bf16 v[114:117], v[26:29], v[230:233], 0
	v_mfma_f32_16x16x32_bf16 v[102:105], v[18:21], v[238:241], 0
	v_mfma_f32_16x16x32_bf16 v[98:101], v[26:29], v[238:241], 0
	v_mfma_f32_16x16x32_bf16 v[150:153], v[22:25], v[182:185], v[150:153]
	v_mfma_f32_16x16x32_bf16 v[146:149], v[30:33], v[182:185], v[146:149]
	v_mfma_f32_16x16x32_bf16 v[134:137], v[22:25], v[226:229], v[134:137]
	v_mfma_f32_16x16x32_bf16 v[130:133], v[30:33], v[226:229], v[130:133]
	v_mfma_f32_16x16x32_bf16 v[118:121], v[22:25], v[234:237], v[118:121]
	v_mfma_f32_16x16x32_bf16 v[114:117], v[30:33], v[234:237], v[114:117]
	v_mfma_f32_16x16x32_bf16 v[102:105], v[22:25], v[242:245], v[102:105]
	v_mfma_f32_16x16x32_bf16 v[98:101], v[30:33], v[242:245], v[98:101]
	s_setprio 0
	s_setprio 1
	v_mfma_f32_16x16x32_bf16 v[142:145], v[46:49], v[178:181], 0
	v_mfma_f32_16x16x32_bf16 v[138:141], v[170:173], v[178:181], 0
	v_mfma_f32_16x16x32_bf16 v[126:129], v[46:49], v[186:189], 0
	v_mfma_f32_16x16x32_bf16 v[122:125], v[170:173], v[186:189], 0
	v_mfma_f32_16x16x32_bf16 v[110:113], v[46:49], v[230:233], 0
	v_mfma_f32_16x16x32_bf16 v[106:109], v[170:173], v[230:233], 0
	v_mfma_f32_16x16x32_bf16 v[94:97], v[46:49], v[238:241], 0
	v_mfma_f32_16x16x32_bf16 v[90:93], v[170:173], v[238:241], 0
	v_mfma_f32_16x16x32_bf16 v[142:145], v[54:57], v[182:185], v[142:145]
	v_mfma_f32_16x16x32_bf16 v[138:141], v[174:177], v[182:185], v[138:141]
	v_mfma_f32_16x16x32_bf16 v[126:129], v[54:57], v[226:229], v[126:129]
	v_mfma_f32_16x16x32_bf16 v[122:125], v[174:177], v[226:229], v[122:125]
	v_mfma_f32_16x16x32_bf16 v[110:113], v[54:57], v[234:237], v[110:113]
	v_mfma_f32_16x16x32_bf16 v[106:109], v[174:177], v[234:237], v[106:109]
	v_mfma_f32_16x16x32_bf16 v[94:97], v[54:57], v[242:245], v[94:97]
	v_mfma_f32_16x16x32_bf16 v[90:93], v[174:177], v[242:245], v[90:93]
	s_setprio 0
	s_barrier
	s_add_i32 s30, s30, s20
	v_lshl_add_u64 v[190:191], s[10:11], 0, v[156:157]
	s_mov_b32 m0, s30
	ds_read_b128 v[178:181], v225 offset:16384
	ds_read_b128 v[182:185], v225 offset:17408
	ds_read_b128 v[186:189], v225 offset:18432
	ds_read_b128 v[226:229], v225 offset:19456
	ds_read_b128 v[230:233], v225 offset:20480
	ds_read_b128 v[234:237], v225 offset:21504
	ds_read_b128 v[238:241], v225 offset:22528
	ds_read_b128 v[242:245], v225 offset:23552
	global_load_lds_dwordx4 v[190:191], off
	s_add_i32 m0, s30, 0x2000
	s_add_u32 s30, s10, 0x40000
	v_lshl_add_u64 v[198:199], s[10:11], 0, v[160:161]
	s_addc_u32 s31, s11, 0
	s_add_i32 s51, s51, s20
	global_load_lds_dwordx4 v[198:199], off
	v_lshl_add_u64 v[200:201], s[30:31], 0, v[156:157]
	s_mov_b32 m0, s51
	v_lshl_add_u64 v[250:251], s[14:15], 0, v[158:159]
	global_load_lds_dwordx4 v[200:201], off
	v_lshl_add_u64 v[200:201], s[30:31], 0, v[160:161]
	s_add_i32 m0, s51, 0x2000
	s_nop 0
	global_load_lds_dwordx4 v[200:201], off
	v_lshl_add_u64 v[200:201], s[14:15], 0, v[154:155]
	s_mov_b32 m0, s21
	s_nop 0
	global_load_lds_dwordx4 v[200:201], off
	s_mov_b32 m0, s45
	s_nop 0
	global_load_lds_dwordx4 v[250:251], off
	s_waitcnt vmcnt(8)
	s_waitcnt lgkmcnt(0)
	s_barrier
; #define PG8_STAGE(bufoff, gbase, voff) do { _Pragma("unroll") for (int _i = 0; _i < 2; ++_i) \
;         __builtin_amdgcn_global_load_lds((const unsigned*)((const char*)(gbase) + (voff)[_i]), (PG8_LAS unsigned*)(lds + (bufoff) + ldsw + _i * 8192), 16, 0, 0); } while (0)
; #define PG8_LDA(dst, b, h) do { _Pragma("unroll") for (int m = 0; m < 4; ++m) _Pragma("unroll") for (int k = 0; k < 2; ++k) dst[m][k] = *(const PG8_LAS bf16x8*)(lds + PG8_SA(b, h) + aoff + m * 2048 + k * 1024); } while (0)
; #define PG8_LDB(dst, b, h) do { _Pragma("unroll") for (int n = 0; n < 2; ++n) _Pragma("unroll") for (int k = 0; k < 2; ++k) dst[n][k] = *(const PG8_LAS bf16x8*)(lds + PG8_SB(b, h) + boff + n * 2048 + k * 1024); } while (0)
; #define PG8_MMA(ai, bj, At, Bt) do { __builtin_amdgcn_s_setprio(1); _Pragma("unroll") for (int m = 0; m < 4; ++m) _Pragma("unroll") for (int n = 0; n < 2; ++n) _Pragma("unroll") for (int k = 0; k < 2; ++k) \
;         acc[ai][bj][m][n] = __builtin_amdgcn_mfma_f32_16x16x32_bf16(Bt[n][k], At[m][k], acc[ai][bj][m][n], 0, 0, 0); __builtin_amdgcn_s_setprio(0); } while (0)
; #define PG8_WAIT_V(n) asm volatile("s_waitcnt vmcnt(" #n ")" ::: "memory")
; #define PG8_WAIT_L(n) asm volatile("s_waitcnt lgkmcnt(" #n ")" ::: "memory")
; #define PG8_BAR __builtin_amdgcn_s_barrier()
; #define PG8_SCHED __builtin_amdgcn_sched_barrier(0)
; template <class Epi, class Sched, bool ALIGN_EPI = false, bool SP2 = false>
; __device__ __forceinline__ void gemm_phase(PG8_LAS unsigned char* lds, const Gemm g, const Sched& S, const Epi& E) {
;     ...
;             PG8_WAIT_V(8); PG8_WAIT_L(0); PG8_BAR; PG8_MMA(1, 0, At, B0); PG8_MMA(1, 1, At, B1); PG8_BAR; PG8_SCHED;
;             PG8_LDB(B0, 1, 0); PG8_LDB(B1, 1, 1); PG8_SCHED; PG8_LDA(At, 1, 0); PG8_STAGE(PG8_SA(0, 1), a2 + hstep, voffA);
;             PG8_WAIT_V(8); PG8_WAIT_L(0); PG8_BAR; PG8_MMA(0, 0, At, B0); PG8_MMA(0, 1, At, B1); PG8_BAR; PG8_SCHED;
	s_setprio 1
	s_waitcnt lgkmcnt(0)
	v_mfma_f32_16x16x32_bf16 v[86:89], v[18:21], v[178:181], 0
	v_mfma_f32_16x16x32_bf16 v[82:85], v[26:29], v[178:181], 0
	v_mfma_f32_16x16x32_bf16 v[70:73], v[18:21], v[186:189], 0
	v_mfma_f32_16x16x32_bf16 v[66:69], v[26:29], v[186:189], 0
	v_mfma_f32_16x16x32_bf16 v[50:53], v[18:21], v[230:233], 0
	v_mfma_f32_16x16x32_bf16 v[42:45], v[26:29], v[230:233], 0
	v_mfma_f32_16x16x32_bf16 v[14:17], v[18:21], v[238:241], 0
	v_mfma_f32_16x16x32_bf16 v[10:13], v[26:29], v[238:241], 0
	v_mfma_f32_16x16x32_bf16 v[86:89], v[22:25], v[182:185], v[86:89]
	v_mfma_f32_16x16x32_bf16 v[82:85], v[30:33], v[182:185], v[82:85]
	v_mfma_f32_16x16x32_bf16 v[70:73], v[22:25], v[226:229], v[70:73]
	v_mfma_f32_16x16x32_bf16 v[66:69], v[30:33], v[226:229], v[66:69]
	v_mfma_f32_16x16x32_bf16 v[50:53], v[22:25], v[234:237], v[50:53]
	v_mfma_f32_16x16x32_bf16 v[42:45], v[30:33], v[234:237], v[42:45]
	v_mfma_f32_16x16x32_bf16 v[14:17], v[22:25], v[242:245], v[14:17]
	v_mfma_f32_16x16x32_bf16 v[10:13], v[30:33], v[242:245], v[10:13]
	s_setprio 0
	s_setprio 1
	v_mfma_f32_16x16x32_bf16 v[38:41], v[46:49], v[230:233], 0
	v_mfma_f32_16x16x32_bf16 v[34:37], v[170:173], v[230:233], 0
	v_mfma_f32_16x16x32_bf16 v[6:9], v[46:49], v[238:241], 0
	v_mfma_f32_16x16x32_bf16 v[2:5], v[170:173], v[238:241], 0
	v_mfma_f32_16x16x32_bf16 v[18:21], v[46:49], v[178:181], 0
	v_mfma_f32_16x16x32_bf16 v[22:25], v[170:173], v[178:181], 0
	v_mfma_f32_16x16x32_bf16 v[26:29], v[46:49], v[186:189], 0
	v_mfma_f32_16x16x32_bf16 v[30:33], v[170:173], v[186:189], 0
	v_mfma_f32_16x16x32_bf16 v[38:41], v[54:57], v[234:237], v[38:41]
	v_mfma_f32_16x16x32_bf16 v[34:37], v[174:177], v[234:237], v[34:37]
	v_mfma_f32_16x16x32_bf16 v[6:9], v[54:57], v[242:245], v[6:9]
	v_mfma_f32_16x16x32_bf16 v[2:5], v[174:177], v[242:245], v[2:5]
	v_mfma_f32_16x16x32_bf16 v[18:21], v[54:57], v[182:185], v[18:21]
	v_mfma_f32_16x16x32_bf16 v[22:25], v[174:177], v[182:185], v[22:25]
	v_mfma_f32_16x16x32_bf16 v[26:29], v[54:57], v[226:229], v[26:29]
	v_mfma_f32_16x16x32_bf16 v[30:33], v[174:177], v[226:229], v[30:33]
	s_setprio 0
	s_barrier
	s_add_i32 s30, 0, 0x18000
	v_add_u32_e32 v0, s30, v204
	s_add_i32 s31, 0, 0x1c000
	ds_read_b128 v[46:49], v0
	ds_read_b128 v[54:57], v0 offset:1024
	ds_read_b128 v[58:61], v0 offset:2048
	ds_read_b128 v[62:65], v0 offset:3072
	v_add_u32_e32 v0, s31, v204
	ds_read_b128 v[170:173], v0
	ds_read_b128 v[174:177], v0 offset:1024
	ds_read_b128 v[178:181], v0 offset:2048
	ds_read_b128 v[182:185], v0 offset:3072
	s_add_u32 s14, s14, 0x40000
	s_addc_u32 s15, s15, 0
	s_mov_b32 m0, s62
	v_lshl_add_u64 v[246:247], s[14:15], 0, v[154:155]
	ds_read_b128 v[74:77], v225 offset:32768
	ds_read_b128 v[78:81], v225 offset:33792
	ds_read_b128 v[186:189], v225 offset:34816
	ds_read_b128 v[226:229], v225 offset:35840
	ds_read_b128 v[230:233], v225 offset:36864
	ds_read_b128 v[234:237], v225 offset:37888
	ds_read_b128 v[238:241], v225 offset:38912
	ds_read_b128 v[242:245], v225 offset:39936
	global_load_lds_dwordx4 v[246:247], off
	v_lshl_add_u64 v[246:247], s[14:15], 0, v[158:159]
	s_mov_b32 m0, s63
	s_nop 0
	global_load_lds_dwordx4 v[246:247], off
	s_waitcnt vmcnt(8)
	s_waitcnt lgkmcnt(0)
	s_barrier
	s_setprio 1
	s_waitcnt lgkmcnt(0)
	v_mfma_f32_16x16x32_bf16 v[150:153], v[46:49], v[74:77], v[150:153]
	v_mfma_f32_16x16x32_bf16 v[146:149], v[58:61], v[74:77], v[146:149]
	v_mfma_f32_16x16x32_bf16 v[134:137], v[46:49], v[186:189], v[134:137]
	v_mfma_f32_16x16x32_bf16 v[130:133], v[58:61], v[186:189], v[130:133]
	v_mfma_f32_16x16x32_bf16 v[118:121], v[46:49], v[230:233], v[118:121]
	v_mfma_f32_16x16x32_bf16 v[114:117], v[58:61], v[230:233], v[114:117]
	v_mfma_f32_16x16x32_bf16 v[102:105], v[46:49], v[238:241], v[102:105]
	v_mfma_f32_16x16x32_bf16 v[98:101], v[58:61], v[238:241], v[98:101]
	v_mfma_f32_16x16x32_bf16 v[150:153], v[54:57], v[78:81], v[150:153]
	v_mfma_f32_16x16x32_bf16 v[146:149], v[62:65], v[78:81], v[146:149]
	v_mfma_f32_16x16x32_bf16 v[134:137], v[54:57], v[226:229], v[134:137]
	v_mfma_f32_16x16x32_bf16 v[130:133], v[62:65], v[226:229], v[130:133]
	v_mfma_f32_16x16x32_bf16 v[118:121], v[54:57], v[234:237], v[118:121]
	v_mfma_f32_16x16x32_bf16 v[114:117], v[62:65], v[234:237], v[114:117]
	v_mfma_f32_16x16x32_bf16 v[102:105], v[54:57], v[242:245], v[102:105]
	v_mfma_f32_16x16x32_bf16 v[98:101], v[62:65], v[242:245], v[98:101]
	s_setprio 0
	s_setprio 1
	v_mfma_f32_16x16x32_bf16 v[142:145], v[170:173], v[74:77], v[142:145]
	v_mfma_f32_16x16x32_bf16 v[74:77], v[178:181], v[74:77], v[138:141]
	v_mfma_f32_16x16x32_bf16 v[138:141], v[182:185], v[78:81], v[74:77]
	v_mfma_f32_16x16x32_bf16 v[74:77], v[170:173], v[186:189], v[126:129]
	v_mfma_f32_16x16x32_bf16 v[126:129], v[174:177], v[226:229], v[74:77]
	v_mfma_f32_16x16x32_bf16 v[74:77], v[178:181], v[186:189], v[122:125]
	v_mfma_f32_16x16x32_bf16 v[122:125], v[182:185], v[226:229], v[74:77]
	v_mfma_f32_16x16x32_bf16 v[74:77], v[170:173], v[230:233], v[110:113]
	v_mfma_f32_16x16x32_bf16 v[110:113], v[174:177], v[234:237], v[74:77]
	v_mfma_f32_16x16x32_bf16 v[74:77], v[178:181], v[230:233], v[106:109]
	v_mfma_f32_16x16x32_bf16 v[106:109], v[182:185], v[234:237], v[74:77]
	v_mfma_f32_16x16x32_bf16 v[74:77], v[170:173], v[238:241], v[94:97]
	v_mfma_f32_16x16x32_bf16 v[94:97], v[174:177], v[242:245], v[74:77]
	v_mfma_f32_16x16x32_bf16 v[74:77], v[178:181], v[238:241], v[90:93]
	v_mfma_f32_16x16x32_bf16 v[142:145], v[174:177], v[78:81], v[142:145]
	v_mfma_f32_16x16x32_bf16 v[90:93], v[182:185], v[242:245], v[74:77]
	s_setprio 0
	s_barrier
; #define PG8_STAGE(bufoff, gbase, voff) do { _Pragma("unroll") for (int _i = 0; _i < 2; ++_i) \
;         __builtin_amdgcn_global_load_lds((const unsigned*)((const char*)(gbase) + (voff)[_i]), (PG8_LAS unsigned*)(lds + (bufoff) + ldsw + _i * 8192), 16, 0, 0); } while (0)
; #define PG8_LDA(dst, b, h) do { _Pragma("unroll") for (int m = 0; m < 4; ++m) _Pragma("unroll") for (int k = 0; k < 2; ++k) dst[m][k] = *(const PG8_LAS bf16x8*)(lds + PG8_SA(b, h) + aoff + m * 2048 + k * 1024); } while (0)
; #define PG8_MMA(ai, bj, At, Bt) do { __builtin_amdgcn_s_setprio(1); _Pragma("unroll") for (int m = 0; m < 4; ++m) _Pragma("unroll") for (int n = 0; n < 2; ++n) _Pragma("unroll") for (int k = 0; k < 2; ++k) \
;         acc[ai][bj][m][n] = __builtin_amdgcn_mfma_f32_16x16x32_bf16(Bt[n][k], At[m][k], acc[ai][bj][m][n], 0, 0, 0); __builtin_amdgcn_s_setprio(0); } while (0)
; #define PG8_WAIT_V(n) asm volatile("s_waitcnt vmcnt(" #n ")" ::: "memory")
; #define PG8_WAIT_L(n) asm volatile("s_waitcnt lgkmcnt(" #n ")" ::: "memory")
; #define PG8_BAR __builtin_amdgcn_s_barrier()
; #define PG8_SCHED __builtin_amdgcn_sched_barrier(0)
; template <class Epi, class Sched, bool ALIGN_EPI = false, bool SP2 = false>
; __device__ __forceinline__ void gemm_phase(PG8_LAS unsigned char* lds, const Gemm g, const Sched& S, const Epi& E) {
;     ...
;             PG8_LDA(At, 1, 1); PG8_STAGE(PG8_SB(1, 0), b3, voffB); PG8_STAGE(PG8_SB(1, 1), b3 + hstep, voffB); PG8_STAGE(PG8_SA(1, 0), a3, voffA);
;             PG8_WAIT_V(8); PG8_WAIT_L(0); PG8_BAR; PG8_MMA(1, 0, At, B0); PG8_MMA(1, 1, At, B1); PG8_BAR; PG8_SCHED;
	s_add_i32 s14, s30, s20
	v_lshl_add_u64 v[78:79], v[190:191], 0, s[0:1]
	s_mov_b32 m0, s14
	s_nop 0
	ds_read_b128 v[74:77], v225 offset:49152
	ds_read_b128 v[186:189], v225 offset:50176
	ds_read_b128 v[226:229], v225 offset:51200
	ds_read_b128 v[230:233], v225 offset:52224
	ds_read_b128 v[234:237], v225 offset:53248
	ds_read_b128 v[238:241], v225 offset:54272
	ds_read_b128 v[242:245], v225 offset:55296
	ds_read_b128 v[246:249], v225 offset:56320
	global_load_lds_dwordx4 v[78:79], off
	s_add_i32 m0, s14, 0x2000
	s_add_u32 s10, s10, 0x40080
	v_lshl_add_u64 v[78:79], v[198:199], 0, s[0:1]
	s_addc_u32 s11, s11, 0
	s_add_i32 s14, s31, s20
	global_load_lds_dwordx4 v[78:79], off
	v_lshl_add_u64 v[78:79], s[10:11], 0, v[156:157]
	s_mov_b32 m0, s14
	s_nop 0
	global_load_lds_dwordx4 v[78:79], off
	v_lshl_add_u64 v[78:79], s[10:11], 0, v[160:161]
	s_add_i32 m0, s14, 0x2000
	s_nop 0
	global_load_lds_dwordx4 v[78:79], off
	v_lshl_add_u64 v[78:79], v[200:201], 0, s[0:1]
	s_mov_b32 m0, s64
	s_nop 0
	global_load_lds_dwordx4 v[78:79], off
	v_lshl_add_u64 v[78:79], v[250:251], 0, s[0:1]
	s_mov_b32 m0, s65
	s_nop 0
	global_load_lds_dwordx4 v[78:79], off
	s_waitcnt vmcnt(8)
	s_waitcnt lgkmcnt(0)
	s_barrier
	s_setprio 1
	s_waitcnt lgkmcnt(0)
	v_mfma_f32_16x16x32_bf16 v[78:81], v[46:49], v[74:77], v[86:89]
	v_mfma_f32_16x16x32_bf16 v[86:89], v[54:57], v[186:189], v[78:81]
	v_mfma_f32_16x16x32_bf16 v[78:81], v[58:61], v[74:77], v[82:85]
	v_mfma_f32_16x16x32_bf16 v[70:73], v[46:49], v[226:229], v[70:73]
	v_mfma_f32_16x16x32_bf16 v[66:69], v[58:61], v[226:229], v[66:69]
	v_mfma_f32_16x16x32_bf16 v[50:53], v[46:49], v[234:237], v[50:53]
	v_mfma_f32_16x16x32_bf16 v[42:45], v[58:61], v[234:237], v[42:45]
	v_mfma_f32_16x16x32_bf16 v[14:17], v[46:49], v[242:245], v[14:17]
	v_mfma_f32_16x16x32_bf16 v[10:13], v[58:61], v[242:245], v[10:13]
	v_mfma_f32_16x16x32_bf16 v[82:85], v[62:65], v[186:189], v[78:81]
	v_mfma_f32_16x16x32_bf16 v[70:73], v[54:57], v[230:233], v[70:73]
	v_mfma_f32_16x16x32_bf16 v[66:69], v[62:65], v[230:233], v[66:69]
	v_mfma_f32_16x16x32_bf16 v[50:53], v[54:57], v[238:241], v[50:53]
	v_mfma_f32_16x16x32_bf16 v[42:45], v[62:65], v[238:241], v[42:45]
	v_mfma_f32_16x16x32_bf16 v[14:17], v[54:57], v[246:249], v[14:17]
	v_mfma_f32_16x16x32_bf16 v[10:13], v[62:65], v[246:249], v[10:13]
	s_setprio 0
	s_setprio 1
	v_mfma_f32_16x16x32_bf16 v[18:21], v[170:173], v[74:77], v[18:21]
	v_mfma_f32_16x16x32_bf16 v[78:81], v[174:177], v[186:189], v[18:21]
	v_mfma_f32_16x16x32_bf16 v[18:21], v[178:181], v[74:77], v[22:25]
	v_mfma_f32_16x16x32_bf16 v[74:77], v[182:185], v[186:189], v[18:21]
	v_mfma_f32_16x16x32_bf16 v[18:21], v[170:173], v[226:229], v[26:29]
	v_mfma_f32_16x16x32_bf16 v[62:65], v[174:177], v[230:233], v[18:21]
	v_mfma_f32_16x16x32_bf16 v[18:21], v[178:181], v[226:229], v[30:33]
	v_mfma_f32_16x16x32_bf16 v[58:61], v[182:185], v[230:233], v[18:21]
	v_mfma_f32_16x16x32_bf16 v[18:21], v[170:173], v[234:237], v[38:41]
	v_mfma_f32_16x16x32_bf16 v[38:41], v[174:177], v[238:241], v[18:21]
	v_mfma_f32_16x16x32_bf16 v[18:21], v[178:181], v[234:237], v[34:37]
	v_mfma_f32_16x16x32_bf16 v[6:9], v[170:173], v[242:245], v[6:9]
	v_mfma_f32_16x16x32_bf16 v[2:5], v[178:181], v[242:245], v[2:5]
	v_mfma_f32_16x16x32_bf16 v[34:37], v[182:185], v[238:241], v[18:21]
	v_mfma_f32_16x16x32_bf16 v[6:9], v[174:177], v[246:249], v[6:9]
	v_mfma_f32_16x16x32_bf16 v[2:5], v[182:185], v[246:249], v[2:5]
	s_setprio 0
	s_barrier
	s_add_i32 s43, s43, 2
	s_add_u32 s8, s8, 0x100
	s_addc_u32 s9, s9, 0
	s_add_u32 s41, s41, 0x100
	s_addc_u32 s42, s42, 0
	s_cmp_gt_u32 s43, 13
	s_cbranch_scc0 .LBB0_188
	s_branch .Lpeel_exit_p1

; #define PG8_BAR __builtin_amdgcn_s_barrier()
; template <class Epi, class Sched, bool ALIGN_EPI = false, bool SP2 = false>
; __device__ __forceinline__ void gemm_phase(PG8_LAS unsigned char* lds, const Gemm g, const Sched& S, const Epi& E) {
;     ...
;         if constexpr (ALIGN_EPI) { if (wr == 0) PG8_BAR; }
.Lpeel_exit_p1:
	s_and_b64 vcc, exec, s[48:49]
	s_cbranch_vccz .LBB0_191
	s_barrier

; #define PG8_STAGE(bufoff, gbase, voff) do { _Pragma("unroll") for (int _i = 0; _i < 2; ++_i) \
;         __builtin_amdgcn_global_load_lds((const unsigned*)((const char*)(gbase) + (voff)[_i]), (PG8_LAS unsigned*)(lds + (bufoff) + ldsw + _i * 8192), 16, 0, 0); } while (0)
; #define PG8_LDA(dst, b, h) do { _Pragma("unroll") for (int m = 0; m < 4; ++m) _Pragma("unroll") for (int k = 0; k < 2; ++k) dst[m][k] = *(const PG8_LAS bf16x8*)(lds + PG8_SA(b, h) + aoff + m * 2048 + k * 1024); } while (0)
; #define PG8_LDB(dst, b, h) do { _Pragma("unroll") for (int n = 0; n < 2; ++n) _Pragma("unroll") for (int k = 0; k < 2; ++k) dst[n][k] = *(const PG8_LAS bf16x8*)(lds + PG8_SB(b, h) + boff + n * 2048 + k * 1024); } while (0)
; #define PG8_MMA(ai, bj, At, Bt) do { __builtin_amdgcn_s_setprio(1); _Pragma("unroll") for (int m = 0; m < 4; ++m) _Pragma("unroll") for (int n = 0; n < 2; ++n) _Pragma("unroll") for (int k = 0; k < 2; ++k) \
;         acc[ai][bj][m][n] = __builtin_amdgcn_mfma_f32_16x16x32_bf16(Bt[n][k], At[m][k], acc[ai][bj][m][n], 0, 0, 0); __builtin_amdgcn_s_setprio(0); } while (0)
; #define PG8_BAR __builtin_amdgcn_s_barrier()
; template <class Epi, class Sched, bool ALIGN_EPI = false, bool SP2 = false>
; __device__ __forceinline__ void gemm_phase(PG8_LAS unsigned char* lds, const Gemm g, const Sched& S, const Epi& E) {
;     ...
;         const bool has_next = S.next(ui + 1, nxt);
;         const char* nA = has_next ? (const char*)g.A + (size_t)nxt.pm * tstep : cA; const char* nB = has_next ? (const char*)g.Bt + (size_t)nxt.pn * tstep : cB;
;         for (int t = 0; t < nt; t += 2) {
;             const bool last = (t == nt - 2);
;             const char* a1 = cA + (size_t)(t + 1) * kstep;
;             const char* a2 = last ? nA : cA + (size_t)(t + 2) * kstep; const char* b2 = last ? nB : cB + (size_t)(t + 2) * kstep;
;             const char* a3 = a2 + kstep; const char* b3 = b2 + kstep;
;             if (last && has_next) S.a_ready(nxt);
;             if constexpr (SP2) {
;             PG8_LDB(B0, 0, 0); PG8_LDB(B1, 0, 1); PG8_SCHED; PG8_LDA(At, 0, 0); PG8_STAGE(PG8_SA(1, 1), a1 + hstep, voffA);
;             PG8_WAIT_V(8); PG8_WAIT_L(0); PG8_BAR; PG8_MMA(0, 0, At, B0); PG8_MMA(0, 1, At, B1); PG8_BAR; PG8_SCHED;
;             PG8_LDA(At, 0, 1); PG8_STAGE(PG8_SB(0, 0), b2, voffB); PG8_STAGE(PG8_SB(0, 1), b2 + hstep, voffB); PG8_STAGE(PG8_SA(0, 0), a2, voffA);
.LBB0_675:
	s_ashr_i32 s15, s14, 31
	s_lshl_b64 s[20:21], s[14:15], 19
	v_readlane_b32 s30, v252, 51
	v_readlane_b32 s31, v252, 52
	s_add_u32 s20, s30, s20
	s_addc_u32 s21, s31, s21
	s_and_b64 s[30:31], s[40:41], exec
	s_cselect_b32 s15, s21, s45
	s_cselect_b32 s34, s20, s44
	s_ashr_i32 s11, s10, 31
	s_lshl_b64 s[30:31], s[10:11], 19
	s_add_u32 s42, s2, s30
	s_addc_u32 s43, s3, s31
	s_and_b64 s[30:31], s[40:41], exec
	s_cselect_b32 s11, s43, s47
	s_cselect_b32 s35, s42, s46
	s_add_u32 s44, s44, 0x40080
	s_addc_u32 s45, s45, 0
	s_add_u32 s59, s46, 0x100
	s_addc_u32 s60, s47, 0
	s_mov_b32 s61, -2
	s_waitcnt lgkmcnt(0)
.Lpeel_p3:
	s_add_u32 s30, s44, 0xfffc0080
	s_addc_u32 s31, s45, -1
	s_add_i32 s62, 0, 0x10000
	s_cmp_eq_u32 s61, 12
	s_cselect_b32 s49, s15, s31
	s_cselect_b32 s48, s34, s30
	s_cselect_b32 s47, s11, s60
	s_cselect_b32 s46, s35, s59
	s_add_i32 s63, 0, 0x14000
	v_add_u32_e32 v134, s62, v185
	v_add_u32_e32 v168, s63, v185
	ds_read_b128 v[114:117], v134
	ds_read_b128 v[118:121], v134 offset:1024
	ds_read_b128 v[126:129], v134 offset:2048
	ds_read_b128 v[134:137], v134 offset:3072
	ds_read_b128 v[146:149], v168
	ds_read_b128 v[150:153], v168 offset:1024
	ds_read_b128 v[164:167], v168 offset:2048
	ds_read_b128 v[168:171], v168 offset:3072
	v_lshl_add_u64 v[210:211], s[44:45], 0, v[160:161]
	s_add_i32 m0, s50, 0xc000
	ds_read_b128 v[172:175], v187
	ds_read_b128 v[176:179], v187 offset:1024
	ds_read_b128 v[180:183], v187 offset:2048
	ds_read_b128 v[188:191], v187 offset:3072
	ds_read_b128 v[198:201], v187 offset:4096
	ds_read_b128 v[202:205], v187 offset:5120
	ds_read_b128 v[206:209], v187 offset:6144
	ds_read_b128 v[222:225], v187 offset:7168
	global_load_lds_dwordx4 v[210:211], off
	v_lshl_add_u64 v[210:211], s[44:45], 0, v[162:163]
	s_add_i32 m0, s50, 0xe000
	s_nop 0
	global_load_lds_dwordx4 v[210:211], off
	s_waitcnt vmcnt(8)
	s_waitcnt lgkmcnt(0)
	s_barrier
	s_setprio 1
	s_waitcnt lgkmcnt(0)
	v_mfma_f32_16x16x32_bf16 v[142:145], v[114:117], v[172:175], 0
	v_mfma_f32_16x16x32_bf16 v[138:141], v[126:129], v[172:175], 0
	v_mfma_f32_16x16x32_bf16 v[110:113], v[114:117], v[180:183], 0
	v_mfma_f32_16x16x32_bf16 v[106:109], v[126:129], v[180:183], 0
	v_mfma_f32_16x16x32_bf16 v[94:97], v[114:117], v[198:201], 0
	v_mfma_f32_16x16x32_bf16 v[90:93], v[126:129], v[198:201], 0
	v_mfma_f32_16x16x32_bf16 v[78:81], v[114:117], v[206:209], 0
	v_mfma_f32_16x16x32_bf16 v[74:77], v[126:129], v[206:209], 0
	v_mfma_f32_16x16x32_bf16 v[142:145], v[118:121], v[176:179], v[142:145]
	v_mfma_f32_16x16x32_bf16 v[138:141], v[134:137], v[176:179], v[138:141]
	v_mfma_f32_16x16x32_bf16 v[110:113], v[118:121], v[188:191], v[110:113]
	v_mfma_f32_16x16x32_bf16 v[106:109], v[134:137], v[188:191], v[106:109]
	v_mfma_f32_16x16x32_bf16 v[94:97], v[118:121], v[202:205], v[94:97]
	v_mfma_f32_16x16x32_bf16 v[90:93], v[134:137], v[202:205], v[90:93]
	v_mfma_f32_16x16x32_bf16 v[78:81], v[118:121], v[222:225], v[78:81]
	v_mfma_f32_16x16x32_bf16 v[74:77], v[134:137], v[222:225], v[74:77]
	s_setprio 0
	s_setprio 1
	v_mfma_f32_16x16x32_bf16 v[130:133], v[146:149], v[172:175], 0
	v_mfma_f32_16x16x32_bf16 v[122:125], v[164:167], v[172:175], 0
	v_mfma_f32_16x16x32_bf16 v[102:105], v[146:149], v[180:183], 0
	v_mfma_f32_16x16x32_bf16 v[98:101], v[164:167], v[180:183], 0
	v_mfma_f32_16x16x32_bf16 v[86:89], v[146:149], v[198:201], 0
	v_mfma_f32_16x16x32_bf16 v[82:85], v[164:167], v[198:201], 0
	v_mfma_f32_16x16x32_bf16 v[70:73], v[146:149], v[206:209], 0
	v_mfma_f32_16x16x32_bf16 v[66:69], v[164:167], v[206:209], 0
	v_mfma_f32_16x16x32_bf16 v[130:133], v[150:153], v[176:179], v[130:133]
	v_mfma_f32_16x16x32_bf16 v[122:125], v[168:171], v[176:179], v[122:125]
	v_mfma_f32_16x16x32_bf16 v[102:105], v[150:153], v[188:191], v[102:105]
	v_mfma_f32_16x16x32_bf16 v[98:101], v[168:171], v[188:191], v[98:101]
	v_mfma_f32_16x16x32_bf16 v[86:89], v[150:153], v[202:205], v[86:89]
	v_mfma_f32_16x16x32_bf16 v[82:85], v[168:171], v[202:205], v[82:85]
	v_mfma_f32_16x16x32_bf16 v[70:73], v[150:153], v[222:225], v[70:73]
	v_mfma_f32_16x16x32_bf16 v[66:69], v[168:171], v[222:225], v[66:69]
	s_setprio 0
	s_barrier
	s_add_i32 s30, s62, s33
	v_lshl_add_u64 v[210:211], s[46:47], 0, v[0:1]
	s_mov_b32 m0, s30
	ds_read_b128 v[172:175], v187 offset:16384
	ds_read_b128 v[176:179], v187 offset:17408
	ds_read_b128 v[180:183], v187 offset:18432
	ds_read_b128 v[188:191], v187 offset:19456
	ds_read_b128 v[198:201], v187 offset:20480
	ds_read_b128 v[202:205], v187 offset:21504
	ds_read_b128 v[206:209], v187 offset:22528
	ds_read_b128 v[222:225], v187 offset:23552
	global_load_lds_dwordx4 v[210:211], off
	s_add_i32 m0, s30, 0x2000
	s_add_u32 s30, s46, 0x40000
	v_lshl_add_u64 v[226:227], s[46:47], 0, v[154:155]
	s_addc_u32 s31, s47, 0
	s_add_i32 s62, s63, s33
	global_load_lds_dwordx4 v[226:227], off
	v_lshl_add_u64 v[228:229], s[30:31], 0, v[0:1]
	s_mov_b32 m0, s62
	v_lshl_add_u64 v[230:231], s[48:49], 0, v[156:157]
	global_load_lds_dwordx4 v[228:229], off
	v_lshl_add_u64 v[228:229], s[30:31], 0, v[154:155]
	s_add_i32 m0, s62, 0x2000
	s_nop 0
	global_load_lds_dwordx4 v[228:229], off
	v_lshl_add_u64 v[228:229], s[48:49], 0, v[158:159]
	s_mov_b32 m0, s50
	s_nop 0
	global_load_lds_dwordx4 v[228:229], off
	s_mov_b32 m0, s51
	s_nop 0
	global_load_lds_dwordx4 v[230:231], off
	s_waitcnt vmcnt(8)
	s_waitcnt lgkmcnt(0)
	s_barrier
; #define PG8_STAGE(bufoff, gbase, voff) do { _Pragma("unroll") for (int _i = 0; _i < 2; ++_i) \
;         __builtin_amdgcn_global_load_lds((const unsigned*)((const char*)(gbase) + (voff)[_i]), (PG8_LAS unsigned*)(lds + (bufoff) + ldsw + _i * 8192), 16, 0, 0); } while (0)
; #define PG8_LDA(dst, b, h) do { _Pragma("unroll") for (int m = 0; m < 4; ++m) _Pragma("unroll") for (int k = 0; k < 2; ++k) dst[m][k] = *(const PG8_LAS bf16x8*)(lds + PG8_SA(b, h) + aoff + m * 2048 + k * 1024); } while (0)
; #define PG8_LDB(dst, b, h) do { _Pragma("unroll") for (int n = 0; n < 2; ++n) _Pragma("unroll") for (int k = 0; k < 2; ++k) dst[n][k] = *(const PG8_LAS bf16x8*)(lds + PG8_SB(b, h) + boff + n * 2048 + k * 1024); } while (0)
; #define PG8_MMA(ai, bj, At, Bt) do { __builtin_amdgcn_s_setprio(1); _Pragma("unroll") for (int m = 0; m < 4; ++m) _Pragma("unroll") for (int n = 0; n < 2; ++n) _Pragma("unroll") for (int k = 0; k < 2; ++k) \
;         acc[ai][bj][m][n] = __builtin_amdgcn_mfma_f32_16x16x32_bf16(Bt[n][k], At[m][k], acc[ai][bj][m][n], 0, 0, 0); __builtin_amdgcn_s_setprio(0); } while (0)
; #define PG8_WAIT_V(n) asm volatile("s_waitcnt vmcnt(" #n ")" ::: "memory")
; #define PG8_WAIT_L(n) asm volatile("s_waitcnt lgkmcnt(" #n ")" ::: "memory")
; #define PG8_BAR __builtin_amdgcn_s_barrier()
; #define PG8_SCHED __builtin_amdgcn_sched_barrier(0)
; template <class Epi, class Sched, bool ALIGN_EPI = false, bool SP2 = false>
; __device__ __forceinline__ void gemm_phase(PG8_LAS unsigned char* lds, const Gemm g, const Sched& S, const Epi& E) {
;     ...
;             PG8_WAIT_V(8); PG8_WAIT_L(0); PG8_BAR; PG8_MMA(1, 0, At, B0); PG8_MMA(1, 1, At, B1); PG8_BAR; PG8_SCHED;
;             PG8_LDB(B0, 1, 0); PG8_LDB(B1, 1, 1); PG8_SCHED; PG8_LDA(At, 1, 0); PG8_STAGE(PG8_SA(0, 1), a2 + hstep, voffA);
;             PG8_WAIT_V(8); PG8_WAIT_L(0); PG8_BAR; PG8_MMA(0, 0, At, B0); PG8_MMA(0, 1, At, B1); PG8_BAR; PG8_SCHED;
	s_setprio 1
	s_waitcnt lgkmcnt(0)
	v_mfma_f32_16x16x32_bf16 v[62:65], v[114:117], v[172:175], 0
	v_mfma_f32_16x16x32_bf16 v[58:61], v[126:129], v[172:175], 0
	v_mfma_f32_16x16x32_bf16 v[46:49], v[114:117], v[180:183], 0
	v_mfma_f32_16x16x32_bf16 v[42:45], v[126:129], v[180:183], 0
	v_mfma_f32_16x16x32_bf16 v[30:33], v[114:117], v[198:201], 0
	v_mfma_f32_16x16x32_bf16 v[26:29], v[126:129], v[198:201], 0
	v_mfma_f32_16x16x32_bf16 v[14:17], v[114:117], v[206:209], 0
	v_mfma_f32_16x16x32_bf16 v[10:13], v[126:129], v[206:209], 0
	v_mfma_f32_16x16x32_bf16 v[62:65], v[118:121], v[176:179], v[62:65]
	v_mfma_f32_16x16x32_bf16 v[58:61], v[134:137], v[176:179], v[58:61]
	v_mfma_f32_16x16x32_bf16 v[46:49], v[118:121], v[188:191], v[46:49]
	v_mfma_f32_16x16x32_bf16 v[42:45], v[134:137], v[188:191], v[42:45]
	v_mfma_f32_16x16x32_bf16 v[30:33], v[118:121], v[202:205], v[30:33]
	v_mfma_f32_16x16x32_bf16 v[26:29], v[134:137], v[202:205], v[26:29]
	v_mfma_f32_16x16x32_bf16 v[14:17], v[118:121], v[222:225], v[14:17]
	v_mfma_f32_16x16x32_bf16 v[10:13], v[134:137], v[222:225], v[10:13]
	s_setprio 0
	s_setprio 1
	v_mfma_f32_16x16x32_bf16 v[54:57], v[146:149], v[172:175], 0
	v_mfma_f32_16x16x32_bf16 v[50:53], v[164:167], v[172:175], 0
	v_mfma_f32_16x16x32_bf16 v[38:41], v[146:149], v[180:183], 0
	v_mfma_f32_16x16x32_bf16 v[34:37], v[164:167], v[180:183], 0
	v_mfma_f32_16x16x32_bf16 v[22:25], v[146:149], v[198:201], 0
	v_mfma_f32_16x16x32_bf16 v[18:21], v[164:167], v[198:201], 0
	v_mfma_f32_16x16x32_bf16 v[6:9], v[146:149], v[206:209], 0
	v_mfma_f32_16x16x32_bf16 v[2:5], v[164:167], v[206:209], 0
	v_mfma_f32_16x16x32_bf16 v[54:57], v[150:153], v[176:179], v[54:57]
	v_mfma_f32_16x16x32_bf16 v[50:53], v[168:171], v[176:179], v[50:53]
	v_mfma_f32_16x16x32_bf16 v[38:41], v[150:153], v[188:191], v[38:41]
	v_mfma_f32_16x16x32_bf16 v[34:37], v[168:171], v[188:191], v[34:37]
	v_mfma_f32_16x16x32_bf16 v[22:25], v[150:153], v[202:205], v[22:25]
	v_mfma_f32_16x16x32_bf16 v[18:21], v[168:171], v[202:205], v[18:21]
	v_mfma_f32_16x16x32_bf16 v[6:9], v[150:153], v[222:225], v[6:9]
	v_mfma_f32_16x16x32_bf16 v[2:5], v[168:171], v[222:225], v[2:5]
	s_setprio 0
	s_barrier
	s_add_i32 s62, 0, 0x18000
	s_add_i32 s63, 0, 0x1c000
	v_add_u32_e32 v134, s62, v185
	v_add_u32_e32 v168, s63, v185
	ds_read_b128 v[114:117], v134
	ds_read_b128 v[118:121], v134 offset:1024
	ds_read_b128 v[126:129], v134 offset:2048
	ds_read_b128 v[134:137], v134 offset:3072
	ds_read_b128 v[146:149], v168
	ds_read_b128 v[150:153], v168 offset:1024
	ds_read_b128 v[164:167], v168 offset:2048
	ds_read_b128 v[168:171], v168 offset:3072
	s_add_u32 s30, s48, 0x40000
	s_addc_u32 s31, s49, 0
	s_mov_b32 m0, s52
	v_lshl_add_u64 v[232:233], s[30:31], 0, v[158:159]
	ds_read_b128 v[172:175], v187 offset:32768
	ds_read_b128 v[176:179], v187 offset:33792
	ds_read_b128 v[180:183], v187 offset:34816
	ds_read_b128 v[188:191], v187 offset:35840
	ds_read_b128 v[198:201], v187 offset:36864
	ds_read_b128 v[202:205], v187 offset:37888
	ds_read_b128 v[206:209], v187 offset:38912
	ds_read_b128 v[222:225], v187 offset:39936
	global_load_lds_dwordx4 v[232:233], off
	v_lshl_add_u64 v[232:233], s[30:31], 0, v[156:157]
	s_mov_b32 m0, s53
	s_nop 0
	global_load_lds_dwordx4 v[232:233], off
	s_waitcnt vmcnt(8)
	s_waitcnt lgkmcnt(0)
	s_barrier
	s_setprio 1
	s_waitcnt lgkmcnt(0)
	v_mfma_f32_16x16x32_bf16 v[142:145], v[114:117], v[172:175], v[142:145]
	v_mfma_f32_16x16x32_bf16 v[138:141], v[126:129], v[172:175], v[138:141]
	v_mfma_f32_16x16x32_bf16 v[110:113], v[114:117], v[180:183], v[110:113]
	v_mfma_f32_16x16x32_bf16 v[106:109], v[126:129], v[180:183], v[106:109]
	v_mfma_f32_16x16x32_bf16 v[94:97], v[114:117], v[198:201], v[94:97]
	v_mfma_f32_16x16x32_bf16 v[90:93], v[126:129], v[198:201], v[90:93]
	v_mfma_f32_16x16x32_bf16 v[78:81], v[114:117], v[206:209], v[78:81]
	v_mfma_f32_16x16x32_bf16 v[74:77], v[126:129], v[206:209], v[74:77]
	v_mfma_f32_16x16x32_bf16 v[142:145], v[118:121], v[176:179], v[142:145]
	v_mfma_f32_16x16x32_bf16 v[138:141], v[134:137], v[176:179], v[138:141]
	v_mfma_f32_16x16x32_bf16 v[110:113], v[118:121], v[188:191], v[110:113]
	v_mfma_f32_16x16x32_bf16 v[106:109], v[134:137], v[188:191], v[106:109]
	v_mfma_f32_16x16x32_bf16 v[94:97], v[118:121], v[202:205], v[94:97]
	v_mfma_f32_16x16x32_bf16 v[90:93], v[134:137], v[202:205], v[90:93]
	v_mfma_f32_16x16x32_bf16 v[78:81], v[118:121], v[222:225], v[78:81]
	v_mfma_f32_16x16x32_bf16 v[74:77], v[134:137], v[222:225], v[74:77]
	s_setprio 0
	s_setprio 1
	v_mfma_f32_16x16x32_bf16 v[130:133], v[146:149], v[172:175], v[130:133]
	v_mfma_f32_16x16x32_bf16 v[122:125], v[164:167], v[172:175], v[122:125]
	v_mfma_f32_16x16x32_bf16 v[102:105], v[146:149], v[180:183], v[102:105]
	v_mfma_f32_16x16x32_bf16 v[98:101], v[164:167], v[180:183], v[98:101]
	v_mfma_f32_16x16x32_bf16 v[86:89], v[146:149], v[198:201], v[86:89]
	v_mfma_f32_16x16x32_bf16 v[82:85], v[164:167], v[198:201], v[82:85]
	v_mfma_f32_16x16x32_bf16 v[70:73], v[146:149], v[206:209], v[70:73]
	v_mfma_f32_16x16x32_bf16 v[66:69], v[164:167], v[206:209], v[66:69]
	v_mfma_f32_16x16x32_bf16 v[130:133], v[150:153], v[176:179], v[130:133]
	v_mfma_f32_16x16x32_bf16 v[122:125], v[168:171], v[176:179], v[122:125]
	v_mfma_f32_16x16x32_bf16 v[102:105], v[150:153], v[188:191], v[102:105]
	v_mfma_f32_16x16x32_bf16 v[98:101], v[168:171], v[188:191], v[98:101]
	v_mfma_f32_16x16x32_bf16 v[86:89], v[150:153], v[202:205], v[86:89]
	v_mfma_f32_16x16x32_bf16 v[82:85], v[168:171], v[202:205], v[82:85]
	v_mfma_f32_16x16x32_bf16 v[70:73], v[150:153], v[222:225], v[70:73]
	v_mfma_f32_16x16x32_bf16 v[66:69], v[168:171], v[222:225], v[66:69]
	s_setprio 0
	s_barrier
; #define PG8_STAGE(bufoff, gbase, voff) do { _Pragma("unroll") for (int _i = 0; _i < 2; ++_i) \
;         __builtin_amdgcn_global_load_lds((const unsigned*)((const char*)(gbase) + (voff)[_i]), (PG8_LAS unsigned*)(lds + (bufoff) + ldsw + _i * 8192), 16, 0, 0); } while (0)
; #define PG8_LDA(dst, b, h) do { _Pragma("unroll") for (int m = 0; m < 4; ++m) _Pragma("unroll") for (int k = 0; k < 2; ++k) dst[m][k] = *(const PG8_LAS bf16x8*)(lds + PG8_SA(b, h) + aoff + m * 2048 + k * 1024); } while (0)
; #define PG8_MMA(ai, bj, At, Bt) do { __builtin_amdgcn_s_setprio(1); _Pragma("unroll") for (int m = 0; m < 4; ++m) _Pragma("unroll") for (int n = 0; n < 2; ++n) _Pragma("unroll") for (int k = 0; k < 2; ++k) \
;         acc[ai][bj][m][n] = __builtin_amdgcn_mfma_f32_16x16x32_bf16(Bt[n][k], At[m][k], acc[ai][bj][m][n], 0, 0, 0); __builtin_amdgcn_s_setprio(0); } while (0)
; #define PG8_WAIT_V(n) asm volatile("s_waitcnt vmcnt(" #n ")" ::: "memory")
; #define PG8_WAIT_L(n) asm volatile("s_waitcnt lgkmcnt(" #n ")" ::: "memory")
; #define PG8_BAR __builtin_amdgcn_s_barrier()
; #define PG8_SCHED __builtin_amdgcn_sched_barrier(0)
; template <class Epi, class Sched, bool ALIGN_EPI = false, bool SP2 = false>
; __device__ __forceinline__ void gemm_phase(PG8_LAS unsigned char* lds, const Gemm g, const Sched& S, const Epi& E) {
;     ...
;             PG8_LDA(At, 1, 1); PG8_STAGE(PG8_SB(1, 0), b3, voffB); PG8_STAGE(PG8_SB(1, 1), b3 + hstep, voffB); PG8_STAGE(PG8_SA(1, 0), a3, voffA);
;             PG8_WAIT_V(8); PG8_WAIT_L(0); PG8_BAR; PG8_MMA(1, 0, At, B0); PG8_MMA(1, 1, At, B1); PG8_BAR; PG8_SCHED;
	s_add_i32 s30, s62, s33
	v_lshl_add_u64 v[210:211], v[210:211], 0, s[0:1]
	s_mov_b32 m0, s30
	ds_read_b128 v[172:175], v187 offset:49152
	ds_read_b128 v[176:179], v187 offset:50176
	ds_read_b128 v[180:183], v187 offset:51200
	ds_read_b128 v[188:191], v187 offset:52224
	ds_read_b128 v[198:201], v187 offset:53248
	ds_read_b128 v[202:205], v187 offset:54272
	ds_read_b128 v[206:209], v187 offset:55296
	ds_read_b128 v[222:225], v187 offset:56320
	global_load_lds_dwordx4 v[210:211], off
	s_add_i32 m0, s30, 0x2000
	s_add_u32 s30, s46, 0x40080
	v_lshl_add_u64 v[210:211], v[226:227], 0, s[0:1]
	s_addc_u32 s31, s47, 0
	s_add_i32 s46, s63, s33
	global_load_lds_dwordx4 v[210:211], off
	v_lshl_add_u64 v[210:211], s[30:31], 0, v[0:1]
	s_mov_b32 m0, s46
	s_nop 0
	global_load_lds_dwordx4 v[210:211], off
	v_lshl_add_u64 v[210:211], s[30:31], 0, v[154:155]
	s_add_i32 m0, s46, 0x2000
	s_nop 0
	global_load_lds_dwordx4 v[210:211], off
	v_lshl_add_u64 v[210:211], v[228:229], 0, s[0:1]
	s_mov_b32 m0, s56
	s_nop 0
	global_load_lds_dwordx4 v[210:211], off
	v_lshl_add_u64 v[210:211], v[230:231], 0, s[0:1]
	s_mov_b32 m0, s57
	s_nop 0
	global_load_lds_dwordx4 v[210:211], off
	s_waitcnt vmcnt(8)
	s_waitcnt lgkmcnt(0)
	s_barrier
	s_setprio 1
	s_waitcnt lgkmcnt(0)
	v_mfma_f32_16x16x32_bf16 v[62:65], v[114:117], v[172:175], v[62:65]
	v_mfma_f32_16x16x32_bf16 v[58:61], v[126:129], v[172:175], v[58:61]
	v_mfma_f32_16x16x32_bf16 v[46:49], v[114:117], v[180:183], v[46:49]
	v_mfma_f32_16x16x32_bf16 v[42:45], v[126:129], v[180:183], v[42:45]
	v_mfma_f32_16x16x32_bf16 v[30:33], v[114:117], v[198:201], v[30:33]
	v_mfma_f32_16x16x32_bf16 v[26:29], v[126:129], v[198:201], v[26:29]
	v_mfma_f32_16x16x32_bf16 v[14:17], v[114:117], v[206:209], v[14:17]
	v_mfma_f32_16x16x32_bf16 v[10:13], v[126:129], v[206:209], v[10:13]
	v_mfma_f32_16x16x32_bf16 v[62:65], v[118:121], v[176:179], v[62:65]
	v_mfma_f32_16x16x32_bf16 v[58:61], v[134:137], v[176:179], v[58:61]
	v_mfma_f32_16x16x32_bf16 v[46:49], v[118:121], v[188:191], v[46:49]
	v_mfma_f32_16x16x32_bf16 v[42:45], v[134:137], v[188:191], v[42:45]
	v_mfma_f32_16x16x32_bf16 v[30:33], v[118:121], v[202:205], v[30:33]
	v_mfma_f32_16x16x32_bf16 v[26:29], v[134:137], v[202:205], v[26:29]
	v_mfma_f32_16x16x32_bf16 v[14:17], v[118:121], v[222:225], v[14:17]
	v_mfma_f32_16x16x32_bf16 v[10:13], v[134:137], v[222:225], v[10:13]
	s_setprio 0
	s_setprio 1
	v_mfma_f32_16x16x32_bf16 v[54:57], v[146:149], v[172:175], v[54:57]
	v_mfma_f32_16x16x32_bf16 v[50:53], v[164:167], v[172:175], v[50:53]
	v_mfma_f32_16x16x32_bf16 v[38:41], v[146:149], v[180:183], v[38:41]
	v_mfma_f32_16x16x32_bf16 v[34:37], v[164:167], v[180:183], v[34:37]
	v_mfma_f32_16x16x32_bf16 v[22:25], v[146:149], v[198:201], v[22:25]
	v_mfma_f32_16x16x32_bf16 v[18:21], v[164:167], v[198:201], v[18:21]
	v_mfma_f32_16x16x32_bf16 v[6:9], v[146:149], v[206:209], v[6:9]
	v_mfma_f32_16x16x32_bf16 v[2:5], v[164:167], v[206:209], v[2:5]
	v_mfma_f32_16x16x32_bf16 v[54:57], v[150:153], v[176:179], v[54:57]
	v_mfma_f32_16x16x32_bf16 v[50:53], v[168:171], v[176:179], v[50:53]
	v_mfma_f32_16x16x32_bf16 v[38:41], v[150:153], v[188:191], v[38:41]
	v_mfma_f32_16x16x32_bf16 v[34:37], v[168:171], v[188:191], v[34:37]
	v_mfma_f32_16x16x32_bf16 v[22:25], v[150:153], v[202:205], v[22:25]
	v_mfma_f32_16x16x32_bf16 v[18:21], v[168:171], v[202:205], v[18:21]
	v_mfma_f32_16x16x32_bf16 v[6:9], v[150:153], v[222:225], v[6:9]
	v_mfma_f32_16x16x32_bf16 v[2:5], v[168:171], v[222:225], v[2:5]
	s_setprio 0
	s_barrier
	s_add_i32 s61, s61, 2
	s_add_u32 s44, s44, 0x100
	s_addc_u32 s45, s45, 0
	s_add_u32 s59, s59, 0x100
	s_addc_u32 s60, s60, 0
	s_cmp_gt_u32 s61, 13
	s_cbranch_scc0 .LBB0_676
	s_branch .Lpeel_exit_p3

; #define PG8_BAR __builtin_amdgcn_s_barrier()
; template <class Epi, class Sched, bool ALIGN_EPI = false, bool SP2 = false>
; __device__ __forceinline__ void gemm_phase(PG8_LAS unsigned char* lds, const Gemm g, const Sched& S, const Epi& E) {
;     ...
;         if constexpr (ALIGN_EPI) { if (wr == 0) PG8_BAR; }
.Lpeel_exit_p3:
	s_and_b64 vcc, exec, s[8:9]
	s_cbranch_vccz .LBB0_679
	s_barrier

; #define PG8_STAGE(bufoff, gbase, voff) do { _Pragma("unroll") for (int _i = 0; _i < 2; ++_i) \
;         __builtin_amdgcn_global_load_lds((const unsigned*)((const char*)(gbase) + (voff)[_i]), (PG8_LAS unsigned*)(lds + (bufoff) + ldsw + _i * 8192), 16, 0, 0); } while (0)
; #define PG8_LDA(dst, b, h) do { _Pragma("unroll") for (int m = 0; m < 4; ++m) _Pragma("unroll") for (int k = 0; k < 2; ++k) dst[m][k] = *(const PG8_LAS bf16x8*)(lds + PG8_SA(b, h) + aoff + m * 2048 + k * 1024); } while (0)
; #define PG8_LDB(dst, b, h) do { _Pragma("unroll") for (int n = 0; n < 2; ++n) _Pragma("unroll") for (int k = 0; k < 2; ++k) dst[n][k] = *(const PG8_LAS bf16x8*)(lds + PG8_SB(b, h) + boff + n * 2048 + k * 1024); } while (0)
; #define PG8_MMA(ai, bj, At, Bt) do { __builtin_amdgcn_s_setprio(1); _Pragma("unroll") for (int m = 0; m < 4; ++m) _Pragma("unroll") for (int n = 0; n < 2; ++n) _Pragma("unroll") for (int k = 0; k < 2; ++k) \
;         acc[ai][bj][m][n] = __builtin_amdgcn_mfma_f32_16x16x32_bf16(Bt[n][k], At[m][k], acc[ai][bj][m][n], 0, 0, 0); __builtin_amdgcn_s_setprio(0); } while (0)
; #define PG8_BAR __builtin_amdgcn_s_barrier()
; template <class Epi, class Sched, bool ALIGN_EPI = false, bool SP2 = false>
; __device__ __forceinline__ void gemm_phase(PG8_LAS unsigned char* lds, const Gemm g, const Sched& S, const Epi& E) {
;     ...
;         const bool has_next = S.next(ui + 1, nxt);
;         const char* nA = has_next ? (const char*)g.A + (size_t)nxt.pm * tstep : cA; const char* nB = has_next ? (const char*)g.Bt + (size_t)nxt.pn * tstep : cB;
;         for (int t = 0; t < nt; t += 2) {
;             const bool last = (t == nt - 2);
;             const char* a1 = cA + (size_t)(t + 1) * kstep;
;             const char* a2 = last ? nA : cA + (size_t)(t + 2) * kstep; const char* b2 = last ? nB : cB + (size_t)(t + 2) * kstep;
;             const char* a3 = a2 + kstep; const char* b3 = b2 + kstep;
;             if (last && has_next) S.a_ready(nxt);
;             if constexpr (SP2) {
;             PG8_LDB(B0, 0, 0); PG8_LDB(B1, 0, 1); PG8_SCHED; PG8_LDA(At, 0, 0); PG8_STAGE(PG8_SA(1, 1), a1 + hstep, voffA);
;             PG8_WAIT_V(8); PG8_WAIT_L(0); PG8_BAR; PG8_MMA(0, 0, At, B0); PG8_MMA(0, 1, At, B1); PG8_BAR; PG8_SCHED;
;             PG8_LDA(At, 0, 1); PG8_STAGE(PG8_SB(0, 0), b2, voffB); PG8_STAGE(PG8_SB(0, 1), b2 + hstep, voffB); PG8_STAGE(PG8_SA(0, 0), a2, voffA);
.LBB0_780:
	s_ashr_i32 s15, s14, 31
	s_lshl_b64 s[20:21], s[14:15], 19
	s_add_u32 s20, s18, s20
	s_addc_u32 s21, s19, s21
	s_and_b64 s[30:31], s[42:43], exec
	s_cselect_b32 s15, s21, s47
	s_cselect_b32 s60, s20, s46
	s_ashr_i32 s11, s10, 31
	s_lshl_b64 s[30:31], s[10:11], 19
	s_add_u32 s44, s2, s30
	s_addc_u32 s45, s3, s31
	s_and_b64 s[30:31], s[42:43], exec
	s_cselect_b32 s11, s45, s49
	s_cselect_b32 s61, s44, s48
	s_add_u32 s46, s46, 0x40080
	s_addc_u32 s47, s47, 0
	s_add_u32 s62, s48, 0x100
	s_addc_u32 s63, s49, 0
	s_mov_b32 s64, -2
.Lpeel_p4:
	s_add_u32 s30, s46, 0xfffc0080
	s_addc_u32 s31, s47, -1
	s_add_i32 s65, 0, 0x10000
	s_cmp_eq_u32 s64, 12
	s_cselect_b32 s51, s15, s31
	s_cselect_b32 s50, s60, s30
	v_add_u32_e32 v152, s65, v157
	s_cselect_b32 s49, s11, s63
	s_cselect_b32 s48, s61, s62
	s_add_i32 s66, 0, 0x14000
	ds_read_b128 v[50:53], v152
	ds_read_b128 v[54:57], v152 offset:1024
	ds_read_b128 v[162:165], v152 offset:2048
	ds_read_b128 v[166:169], v152 offset:3072
	v_add_u32_e32 v152, s66, v157
	ds_read_b128 v[170:173], v152
	ds_read_b128 v[174:177], v152 offset:1024
	ds_read_b128 v[178:181], v152 offset:2048
	ds_read_b128 v[182:185], v152 offset:3072
	v_lshl_add_u64 v[152:153], s[46:47], 0, v[148:149]
	s_add_i32 m0, s52, 0xc000
	ds_read_b128 v[186:189], v160
	ds_read_b128 v[198:201], v160 offset:1024
	ds_read_b128 v[202:205], v160 offset:2048
	ds_read_b128 v[206:209], v160 offset:3072
	ds_read_b128 v[222:225], v160 offset:4096
	ds_read_b128 v[226:229], v160 offset:5120
	ds_read_b128 v[230:233], v160 offset:6144
	ds_read_b128 v[234:237], v160 offset:7168
	global_load_lds_dwordx4 v[152:153], off
	v_lshl_add_u64 v[152:153], s[46:47], 0, v[150:151]
	s_add_i32 m0, s52, 0xe000
	s_nop 0
	global_load_lds_dwordx4 v[152:153], off
	s_waitcnt vmcnt(8)
	s_waitcnt lgkmcnt(0)
	s_barrier
	s_setprio 1
	s_waitcnt lgkmcnt(0)
	v_mfma_f32_16x16x32_bf16 v[134:137], v[50:53], v[186:189], 0
	v_mfma_f32_16x16x32_bf16 v[126:129], v[162:165], v[186:189], 0
	v_mfma_f32_16x16x32_bf16 v[118:121], v[50:53], v[202:205], 0
	v_mfma_f32_16x16x32_bf16 v[110:113], v[162:165], v[202:205], 0
	v_mfma_f32_16x16x32_bf16 v[102:105], v[50:53], v[222:225], 0
	v_mfma_f32_16x16x32_bf16 v[94:97], v[162:165], v[222:225], 0
	v_mfma_f32_16x16x32_bf16 v[86:89], v[50:53], v[230:233], 0
	v_mfma_f32_16x16x32_bf16 v[78:81], v[162:165], v[230:233], 0
	v_mfma_f32_16x16x32_bf16 v[134:137], v[54:57], v[198:201], v[134:137]
	v_mfma_f32_16x16x32_bf16 v[126:129], v[166:169], v[198:201], v[126:129]
	v_mfma_f32_16x16x32_bf16 v[118:121], v[54:57], v[206:209], v[118:121]
	v_mfma_f32_16x16x32_bf16 v[110:113], v[166:169], v[206:209], v[110:113]
	v_mfma_f32_16x16x32_bf16 v[102:105], v[54:57], v[226:229], v[102:105]
	v_mfma_f32_16x16x32_bf16 v[94:97], v[166:169], v[226:229], v[94:97]
	v_mfma_f32_16x16x32_bf16 v[86:89], v[54:57], v[234:237], v[86:89]
	v_mfma_f32_16x16x32_bf16 v[78:81], v[166:169], v[234:237], v[78:81]
	s_setprio 0
	s_setprio 1
	v_mfma_f32_16x16x32_bf16 v[130:133], v[170:173], v[186:189], 0
	v_mfma_f32_16x16x32_bf16 v[122:125], v[178:181], v[186:189], 0
	v_mfma_f32_16x16x32_bf16 v[114:117], v[170:173], v[202:205], 0
	v_mfma_f32_16x16x32_bf16 v[106:109], v[178:181], v[202:205], 0
	v_mfma_f32_16x16x32_bf16 v[98:101], v[170:173], v[222:225], 0
	v_mfma_f32_16x16x32_bf16 v[90:93], v[178:181], v[222:225], 0
	v_mfma_f32_16x16x32_bf16 v[82:85], v[170:173], v[230:233], 0
	v_mfma_f32_16x16x32_bf16 v[74:77], v[178:181], v[230:233], 0
	v_mfma_f32_16x16x32_bf16 v[130:133], v[174:177], v[198:201], v[130:133]
	v_mfma_f32_16x16x32_bf16 v[122:125], v[182:185], v[198:201], v[122:125]
	v_mfma_f32_16x16x32_bf16 v[114:117], v[174:177], v[206:209], v[114:117]
	v_mfma_f32_16x16x32_bf16 v[106:109], v[182:185], v[206:209], v[106:109]
	v_mfma_f32_16x16x32_bf16 v[98:101], v[174:177], v[226:229], v[98:101]
	v_mfma_f32_16x16x32_bf16 v[90:93], v[182:185], v[226:229], v[90:93]
	v_mfma_f32_16x16x32_bf16 v[82:85], v[174:177], v[234:237], v[82:85]
	v_mfma_f32_16x16x32_bf16 v[74:77], v[182:185], v[234:237], v[74:77]
	s_setprio 0
	s_barrier
	s_add_i32 s30, s65, s33
	v_lshl_add_u64 v[152:153], s[48:49], 0, v[140:141]
	s_mov_b32 m0, s30
	ds_read_b128 v[186:189], v160 offset:16384
	ds_read_b128 v[198:201], v160 offset:17408
	ds_read_b128 v[202:205], v160 offset:18432
	ds_read_b128 v[206:209], v160 offset:19456
	ds_read_b128 v[222:225], v160 offset:20480
	ds_read_b128 v[226:229], v160 offset:21504
	ds_read_b128 v[230:233], v160 offset:22528
	ds_read_b128 v[234:237], v160 offset:23552
	global_load_lds_dwordx4 v[152:153], off
	s_add_i32 m0, s30, 0x2000
	s_add_u32 s30, s48, 0x40000
	v_lshl_add_u64 v[190:191], s[48:49], 0, v[144:145]
	s_addc_u32 s31, s49, 0
	s_add_i32 s65, s66, s33
	global_load_lds_dwordx4 v[190:191], off
	v_lshl_add_u64 v[210:211], s[30:31], 0, v[140:141]
	s_mov_b32 m0, s65
	v_lshl_add_u64 v[238:239], s[50:51], 0, v[142:143]
	global_load_lds_dwordx4 v[210:211], off
	v_lshl_add_u64 v[210:211], s[30:31], 0, v[144:145]
	s_add_i32 m0, s65, 0x2000
	s_nop 0
	global_load_lds_dwordx4 v[210:211], off
	v_lshl_add_u64 v[210:211], s[50:51], 0, v[138:139]
	s_mov_b32 m0, s52
	s_nop 0
	global_load_lds_dwordx4 v[210:211], off
	s_mov_b32 m0, s53
	s_nop 0
	global_load_lds_dwordx4 v[238:239], off
	s_waitcnt vmcnt(8)
	s_waitcnt lgkmcnt(0)
	s_barrier
; #define PG8_STAGE(bufoff, gbase, voff) do { _Pragma("unroll") for (int _i = 0; _i < 2; ++_i) \
;         __builtin_amdgcn_global_load_lds((const unsigned*)((const char*)(gbase) + (voff)[_i]), (PG8_LAS unsigned*)(lds + (bufoff) + ldsw + _i * 8192), 16, 0, 0); } while (0)
; #define PG8_LDA(dst, b, h) do { _Pragma("unroll") for (int m = 0; m < 4; ++m) _Pragma("unroll") for (int k = 0; k < 2; ++k) dst[m][k] = *(const PG8_LAS bf16x8*)(lds + PG8_SA(b, h) + aoff + m * 2048 + k * 1024); } while (0)
; #define PG8_LDB(dst, b, h) do { _Pragma("unroll") for (int n = 0; n < 2; ++n) _Pragma("unroll") for (int k = 0; k < 2; ++k) dst[n][k] = *(const PG8_LAS bf16x8*)(lds + PG8_SB(b, h) + boff + n * 2048 + k * 1024); } while (0)
; #define PG8_MMA(ai, bj, At, Bt) do { __builtin_amdgcn_s_setprio(1); _Pragma("unroll") for (int m = 0; m < 4; ++m) _Pragma("unroll") for (int n = 0; n < 2; ++n) _Pragma("unroll") for (int k = 0; k < 2; ++k) \
;         acc[ai][bj][m][n] = __builtin_amdgcn_mfma_f32_16x16x32_bf16(Bt[n][k], At[m][k], acc[ai][bj][m][n], 0, 0, 0); __builtin_amdgcn_s_setprio(0); } while (0)
; #define PG8_WAIT_V(n) asm volatile("s_waitcnt vmcnt(" #n ")" ::: "memory")
; #define PG8_WAIT_L(n) asm volatile("s_waitcnt lgkmcnt(" #n ")" ::: "memory")
; #define PG8_BAR __builtin_amdgcn_s_barrier()
; #define PG8_SCHED __builtin_amdgcn_sched_barrier(0)
; template <class Epi, class Sched, bool ALIGN_EPI = false, bool SP2 = false>
; __device__ __forceinline__ void gemm_phase(PG8_LAS unsigned char* lds, const Gemm g, const Sched& S, const Epi& E) {
;     ...
;             PG8_WAIT_V(8); PG8_WAIT_L(0); PG8_BAR; PG8_MMA(1, 0, At, B0); PG8_MMA(1, 1, At, B1); PG8_BAR; PG8_SCHED;
;             PG8_LDB(B0, 1, 0); PG8_LDB(B1, 1, 1); PG8_SCHED; PG8_LDA(At, 1, 0); PG8_STAGE(PG8_SA(0, 1), a2 + hstep, voffA);
;             PG8_WAIT_V(8); PG8_WAIT_L(0); PG8_BAR; PG8_MMA(0, 0, At, B0); PG8_MMA(0, 1, At, B1); PG8_BAR; PG8_SCHED;
	s_setprio 1
	s_waitcnt lgkmcnt(0)
	v_mfma_f32_16x16x32_bf16 v[70:73], v[50:53], v[186:189], 0
	v_mfma_f32_16x16x32_bf16 v[62:65], v[162:165], v[186:189], 0
	v_mfma_f32_16x16x32_bf16 v[46:49], v[50:53], v[202:205], 0
	v_mfma_f32_16x16x32_bf16 v[38:41], v[162:165], v[202:205], 0
	v_mfma_f32_16x16x32_bf16 v[30:33], v[50:53], v[222:225], 0
	v_mfma_f32_16x16x32_bf16 v[22:25], v[162:165], v[222:225], 0
	v_mfma_f32_16x16x32_bf16 v[14:17], v[50:53], v[230:233], 0
	v_mfma_f32_16x16x32_bf16 v[6:9], v[162:165], v[230:233], 0
	v_mfma_f32_16x16x32_bf16 v[70:73], v[54:57], v[198:201], v[70:73]
	v_mfma_f32_16x16x32_bf16 v[62:65], v[166:169], v[198:201], v[62:65]
	v_mfma_f32_16x16x32_bf16 v[46:49], v[54:57], v[206:209], v[46:49]
	v_mfma_f32_16x16x32_bf16 v[38:41], v[166:169], v[206:209], v[38:41]
	v_mfma_f32_16x16x32_bf16 v[30:33], v[54:57], v[226:229], v[30:33]
	v_mfma_f32_16x16x32_bf16 v[22:25], v[166:169], v[226:229], v[22:25]
	v_mfma_f32_16x16x32_bf16 v[14:17], v[54:57], v[234:237], v[14:17]
	v_mfma_f32_16x16x32_bf16 v[6:9], v[166:169], v[234:237], v[6:9]
	s_setprio 0
	s_setprio 1
	v_mfma_f32_16x16x32_bf16 v[42:45], v[170:173], v[202:205], 0
	v_mfma_f32_16x16x32_bf16 v[34:37], v[178:181], v[202:205], 0
	v_mfma_f32_16x16x32_bf16 v[26:29], v[170:173], v[222:225], 0
	v_mfma_f32_16x16x32_bf16 v[18:21], v[178:181], v[222:225], 0
	v_mfma_f32_16x16x32_bf16 v[10:13], v[170:173], v[230:233], 0
	v_mfma_f32_16x16x32_bf16 v[2:5], v[178:181], v[230:233], 0
	v_mfma_f32_16x16x32_bf16 v[50:53], v[170:173], v[186:189], 0
	v_mfma_f32_16x16x32_bf16 v[54:57], v[178:181], v[186:189], 0
	v_mfma_f32_16x16x32_bf16 v[42:45], v[174:177], v[206:209], v[42:45]
	v_mfma_f32_16x16x32_bf16 v[34:37], v[182:185], v[206:209], v[34:37]
	v_mfma_f32_16x16x32_bf16 v[26:29], v[174:177], v[226:229], v[26:29]
	v_mfma_f32_16x16x32_bf16 v[18:21], v[182:185], v[226:229], v[18:21]
	v_mfma_f32_16x16x32_bf16 v[10:13], v[174:177], v[234:237], v[10:13]
	v_mfma_f32_16x16x32_bf16 v[2:5], v[182:185], v[234:237], v[2:5]
	v_mfma_f32_16x16x32_bf16 v[50:53], v[174:177], v[198:201], v[50:53]
	v_mfma_f32_16x16x32_bf16 v[54:57], v[182:185], v[198:201], v[54:57]
	s_setprio 0
	s_barrier
	s_add_i32 s65, 0, 0x18000
	v_add_u32_e32 v161, s65, v157
	s_add_i32 s66, 0, 0x1c000
	ds_read_b128 v[58:61], v161
	ds_read_b128 v[66:69], v161 offset:1024
	ds_read_b128 v[162:165], v161 offset:2048
	ds_read_b128 v[166:169], v161 offset:3072
	v_add_u32_e32 v161, s66, v157
	ds_read_b128 v[170:173], v161
	ds_read_b128 v[174:177], v161 offset:1024
	ds_read_b128 v[178:181], v161 offset:2048
	ds_read_b128 v[182:185], v161 offset:3072
	s_add_u32 s30, s50, 0x40000
	s_addc_u32 s31, s51, 0
	s_mov_b32 m0, s54
	v_lshl_add_u64 v[240:241], s[30:31], 0, v[138:139]
	ds_read_b128 v[186:189], v160 offset:32768
	ds_read_b128 v[198:201], v160 offset:33792
	ds_read_b128 v[202:205], v160 offset:34816
	ds_read_b128 v[206:209], v160 offset:35840
	ds_read_b128 v[222:225], v160 offset:36864
	ds_read_b128 v[226:229], v160 offset:37888
	ds_read_b128 v[230:233], v160 offset:38912
	ds_read_b128 v[234:237], v160 offset:39936
	global_load_lds_dwordx4 v[240:241], off
	v_lshl_add_u64 v[240:241], s[30:31], 0, v[142:143]
	s_mov_b32 m0, s55
	s_nop 0
	global_load_lds_dwordx4 v[240:241], off
	s_waitcnt vmcnt(8)
	s_waitcnt lgkmcnt(0)
	s_barrier
	s_setprio 1
	s_waitcnt lgkmcnt(0)
	v_mfma_f32_16x16x32_bf16 v[134:137], v[58:61], v[186:189], v[134:137]
	v_mfma_f32_16x16x32_bf16 v[126:129], v[162:165], v[186:189], v[126:129]
	v_mfma_f32_16x16x32_bf16 v[118:121], v[58:61], v[202:205], v[118:121]
	v_mfma_f32_16x16x32_bf16 v[110:113], v[162:165], v[202:205], v[110:113]
	v_mfma_f32_16x16x32_bf16 v[102:105], v[58:61], v[222:225], v[102:105]
	v_mfma_f32_16x16x32_bf16 v[94:97], v[162:165], v[222:225], v[94:97]
	v_mfma_f32_16x16x32_bf16 v[86:89], v[58:61], v[230:233], v[86:89]
	v_mfma_f32_16x16x32_bf16 v[78:81], v[162:165], v[230:233], v[78:81]
	v_mfma_f32_16x16x32_bf16 v[134:137], v[66:69], v[198:201], v[134:137]
	v_mfma_f32_16x16x32_bf16 v[126:129], v[166:169], v[198:201], v[126:129]
	v_mfma_f32_16x16x32_bf16 v[118:121], v[66:69], v[206:209], v[118:121]
	v_mfma_f32_16x16x32_bf16 v[110:113], v[166:169], v[206:209], v[110:113]
	v_mfma_f32_16x16x32_bf16 v[102:105], v[66:69], v[226:229], v[102:105]
	v_mfma_f32_16x16x32_bf16 v[94:97], v[166:169], v[226:229], v[94:97]
	v_mfma_f32_16x16x32_bf16 v[86:89], v[66:69], v[234:237], v[86:89]
	v_mfma_f32_16x16x32_bf16 v[78:81], v[166:169], v[234:237], v[78:81]
	s_setprio 0
	s_setprio 1
	v_mfma_f32_16x16x32_bf16 v[130:133], v[170:173], v[186:189], v[130:133]
	v_mfma_f32_16x16x32_bf16 v[122:125], v[178:181], v[186:189], v[122:125]
	v_mfma_f32_16x16x32_bf16 v[114:117], v[170:173], v[202:205], v[114:117]
	v_mfma_f32_16x16x32_bf16 v[106:109], v[178:181], v[202:205], v[106:109]
	v_mfma_f32_16x16x32_bf16 v[98:101], v[170:173], v[222:225], v[98:101]
	v_mfma_f32_16x16x32_bf16 v[90:93], v[178:181], v[222:225], v[90:93]
	v_mfma_f32_16x16x32_bf16 v[82:85], v[170:173], v[230:233], v[82:85]
	v_mfma_f32_16x16x32_bf16 v[74:77], v[178:181], v[230:233], v[74:77]
	v_mfma_f32_16x16x32_bf16 v[130:133], v[174:177], v[198:201], v[130:133]
	v_mfma_f32_16x16x32_bf16 v[122:125], v[182:185], v[198:201], v[122:125]
	v_mfma_f32_16x16x32_bf16 v[114:117], v[174:177], v[206:209], v[114:117]
	v_mfma_f32_16x16x32_bf16 v[106:109], v[182:185], v[206:209], v[106:109]
	v_mfma_f32_16x16x32_bf16 v[98:101], v[174:177], v[226:229], v[98:101]
	v_mfma_f32_16x16x32_bf16 v[90:93], v[182:185], v[226:229], v[90:93]
	v_mfma_f32_16x16x32_bf16 v[82:85], v[174:177], v[234:237], v[82:85]
	v_mfma_f32_16x16x32_bf16 v[74:77], v[182:185], v[234:237], v[74:77]
	s_setprio 0
	s_barrier
; #define PG8_STAGE(bufoff, gbase, voff) do { _Pragma("unroll") for (int _i = 0; _i < 2; ++_i) \
;         __builtin_amdgcn_global_load_lds((const unsigned*)((const char*)(gbase) + (voff)[_i]), (PG8_LAS unsigned*)(lds + (bufoff) + ldsw + _i * 8192), 16, 0, 0); } while (0)
; #define PG8_LDA(dst, b, h) do { _Pragma("unroll") for (int m = 0; m < 4; ++m) _Pragma("unroll") for (int k = 0; k < 2; ++k) dst[m][k] = *(const PG8_LAS bf16x8*)(lds + PG8_SA(b, h) + aoff + m * 2048 + k * 1024); } while (0)
; #define PG8_MMA(ai, bj, At, Bt) do { __builtin_amdgcn_s_setprio(1); _Pragma("unroll") for (int m = 0; m < 4; ++m) _Pragma("unroll") for (int n = 0; n < 2; ++n) _Pragma("unroll") for (int k = 0; k < 2; ++k) \
;         acc[ai][bj][m][n] = __builtin_amdgcn_mfma_f32_16x16x32_bf16(Bt[n][k], At[m][k], acc[ai][bj][m][n], 0, 0, 0); __builtin_amdgcn_s_setprio(0); } while (0)
; #define PG8_WAIT_V(n) asm volatile("s_waitcnt vmcnt(" #n ")" ::: "memory")
; #define PG8_WAIT_L(n) asm volatile("s_waitcnt lgkmcnt(" #n ")" ::: "memory")
; #define PG8_BAR __builtin_amdgcn_s_barrier()
; #define PG8_SCHED __builtin_amdgcn_sched_barrier(0)
; template <class Epi, class Sched, bool ALIGN_EPI = false, bool SP2 = false>
; __device__ __forceinline__ void gemm_phase(PG8_LAS unsigned char* lds, const Gemm g, const Sched& S, const Epi& E) {
;     ...
;             PG8_LDA(At, 1, 1); PG8_STAGE(PG8_SB(1, 0), b3, voffB); PG8_STAGE(PG8_SB(1, 1), b3 + hstep, voffB); PG8_STAGE(PG8_SA(1, 0), a3, voffA);
;             PG8_WAIT_V(8); PG8_WAIT_L(0); PG8_BAR; PG8_MMA(1, 0, At, B0); PG8_MMA(1, 1, At, B1); PG8_BAR; PG8_SCHED;
	s_add_i32 s30, s65, s33
	v_lshl_add_u64 v[152:153], v[152:153], 0, s[0:1]
	s_mov_b32 m0, s30
	ds_read_b128 v[186:189], v160 offset:49152
	ds_read_b128 v[198:201], v160 offset:50176
	ds_read_b128 v[202:205], v160 offset:51200
	ds_read_b128 v[206:209], v160 offset:52224
	ds_read_b128 v[222:225], v160 offset:53248
	ds_read_b128 v[226:229], v160 offset:54272
	ds_read_b128 v[230:233], v160 offset:55296
	ds_read_b128 v[234:237], v160 offset:56320
	global_load_lds_dwordx4 v[152:153], off
	s_add_i32 m0, s30, 0x2000
	s_add_u32 s30, s48, 0x40080
	v_lshl_add_u64 v[152:153], v[190:191], 0, s[0:1]
	s_addc_u32 s31, s49, 0
	s_add_i32 s48, s66, s33
	global_load_lds_dwordx4 v[152:153], off
	v_lshl_add_u64 v[152:153], s[30:31], 0, v[140:141]
	s_mov_b32 m0, s48
	s_nop 0
	global_load_lds_dwordx4 v[152:153], off
	v_lshl_add_u64 v[152:153], s[30:31], 0, v[144:145]
	s_add_i32 m0, s48, 0x2000
	s_nop 0
	global_load_lds_dwordx4 v[152:153], off
	v_lshl_add_u64 v[152:153], v[210:211], 0, s[0:1]
	s_mov_b32 m0, s56
	s_nop 0
	global_load_lds_dwordx4 v[152:153], off
	v_lshl_add_u64 v[152:153], v[238:239], 0, s[0:1]
	s_mov_b32 m0, s57
	s_nop 0
	global_load_lds_dwordx4 v[152:153], off
	s_waitcnt vmcnt(8)
	s_waitcnt lgkmcnt(0)
	s_barrier
	s_setprio 1
	s_waitcnt lgkmcnt(0)
	v_mfma_f32_16x16x32_bf16 v[70:73], v[58:61], v[186:189], v[70:73]
	v_mfma_f32_16x16x32_bf16 v[62:65], v[162:165], v[186:189], v[62:65]
	v_mfma_f32_16x16x32_bf16 v[46:49], v[58:61], v[202:205], v[46:49]
	v_mfma_f32_16x16x32_bf16 v[38:41], v[162:165], v[202:205], v[38:41]
	v_mfma_f32_16x16x32_bf16 v[30:33], v[58:61], v[222:225], v[30:33]
	v_mfma_f32_16x16x32_bf16 v[22:25], v[162:165], v[222:225], v[22:25]
	v_mfma_f32_16x16x32_bf16 v[14:17], v[58:61], v[230:233], v[14:17]
	v_mfma_f32_16x16x32_bf16 v[6:9], v[162:165], v[230:233], v[6:9]
	v_mfma_f32_16x16x32_bf16 v[70:73], v[66:69], v[198:201], v[70:73]
	v_mfma_f32_16x16x32_bf16 v[62:65], v[166:169], v[198:201], v[62:65]
	v_mfma_f32_16x16x32_bf16 v[46:49], v[66:69], v[206:209], v[46:49]
	v_mfma_f32_16x16x32_bf16 v[38:41], v[166:169], v[206:209], v[38:41]
	v_mfma_f32_16x16x32_bf16 v[30:33], v[66:69], v[226:229], v[30:33]
	v_mfma_f32_16x16x32_bf16 v[22:25], v[166:169], v[226:229], v[22:25]
	v_mfma_f32_16x16x32_bf16 v[14:17], v[66:69], v[234:237], v[14:17]
	v_mfma_f32_16x16x32_bf16 v[6:9], v[166:169], v[234:237], v[6:9]
	s_setprio 0
	s_setprio 1
	v_mfma_f32_16x16x32_bf16 v[50:53], v[170:173], v[186:189], v[50:53]
	v_mfma_f32_16x16x32_bf16 v[66:69], v[174:177], v[198:201], v[50:53]
	v_mfma_f32_16x16x32_bf16 v[50:53], v[178:181], v[186:189], v[54:57]
	v_mfma_f32_16x16x32_bf16 v[42:45], v[170:173], v[202:205], v[42:45]
	v_mfma_f32_16x16x32_bf16 v[34:37], v[178:181], v[202:205], v[34:37]
	v_mfma_f32_16x16x32_bf16 v[26:29], v[170:173], v[222:225], v[26:29]
	v_mfma_f32_16x16x32_bf16 v[18:21], v[178:181], v[222:225], v[18:21]
	v_mfma_f32_16x16x32_bf16 v[10:13], v[170:173], v[230:233], v[10:13]
	v_mfma_f32_16x16x32_bf16 v[2:5], v[178:181], v[230:233], v[2:5]
	v_mfma_f32_16x16x32_bf16 v[58:61], v[182:185], v[198:201], v[50:53]
	v_mfma_f32_16x16x32_bf16 v[42:45], v[174:177], v[206:209], v[42:45]
	v_mfma_f32_16x16x32_bf16 v[34:37], v[182:185], v[206:209], v[34:37]
	v_mfma_f32_16x16x32_bf16 v[26:29], v[174:177], v[226:229], v[26:29]
	v_mfma_f32_16x16x32_bf16 v[18:21], v[182:185], v[226:229], v[18:21]
	v_mfma_f32_16x16x32_bf16 v[10:13], v[174:177], v[234:237], v[10:13]
	v_mfma_f32_16x16x32_bf16 v[2:5], v[182:185], v[234:237], v[2:5]
	s_setprio 0
	s_barrier
	s_add_i32 s64, s64, 2
	s_add_u32 s46, s46, 0x100
	s_addc_u32 s47, s47, 0
	s_add_u32 s62, s62, 0x100
	s_addc_u32 s63, s63, 0
	s_cmp_gt_u32 s64, 13
	s_cbranch_scc0 .LBB0_781
	s_branch .Lpeel_exit_p4

; #define PG8_STAGE(bufoff, gbase, voff) do { _Pragma("unroll") for (int _i = 0; _i < 2; ++_i) \
;         __builtin_amdgcn_global_load_lds((const unsigned*)((const char*)(gbase) + (voff)[_i]), (PG8_LAS unsigned*)(lds + (bufoff) + ldsw + _i * 8192), 16, 0, 0); } while (0)
; #define PG8_LDA(dst, b, h) do { _Pragma("unroll") for (int m = 0; m < 4; ++m) _Pragma("unroll") for (int k = 0; k < 2; ++k) dst[m][k] = *(const PG8_LAS bf16x8*)(lds + PG8_SA(b, h) + aoff + m * 2048 + k * 1024); } while (0)
; #define PG8_LDB(dst, b, h) do { _Pragma("unroll") for (int n = 0; n < 2; ++n) _Pragma("unroll") for (int k = 0; k < 2; ++k) dst[n][k] = *(const PG8_LAS bf16x8*)(lds + PG8_SB(b, h) + boff + n * 2048 + k * 1024); } while (0)
; #define PG8_MMA(ai, bj, At, Bt) do { __builtin_amdgcn_s_setprio(1); _Pragma("unroll") for (int m = 0; m < 4; ++m) _Pragma("unroll") for (int n = 0; n < 2; ++n) _Pragma("unroll") for (int k = 0; k < 2; ++k) \
;         acc[ai][bj][m][n] = __builtin_amdgcn_mfma_f32_16x16x32_bf16(Bt[n][k], At[m][k], acc[ai][bj][m][n], 0, 0, 0); __builtin_amdgcn_s_setprio(0); } while (0)
; #define PG8_WAIT_V(n) asm volatile("s_waitcnt vmcnt(" #n ")" ::: "memory")
; #define PG8_BAR __builtin_amdgcn_s_barrier()
; template <class Epi, class Sched, bool ALIGN_EPI = false, bool SP2 = false>
; __device__ __forceinline__ void gemm_phase(PG8_LAS unsigned char* lds, const Gemm g, const Sched& S, const Epi& E) {
;     ...
;         for (int t = 0; t < nt; t += 2) {
;             const bool last = (t == nt - 2);
;             const char* a1 = cA + (size_t)(t + 1) * kstep;
;             const char* a2 = last ? nA : cA + (size_t)(t + 2) * kstep; const char* b2 = last ? nB : cB + (size_t)(t + 2) * kstep;
;             const char* a3 = a2 + kstep; const char* b3 = b2 + kstep;
;             if (last && has_next) S.a_ready(nxt);
;             if constexpr (SP2) {
;             PG8_LDB(B0, 0, 0); PG8_LDB(B1, 0, 1); PG8_SCHED; PG8_LDA(At, 0, 0); PG8_STAGE(PG8_SA(1, 1), a1 + hstep, voffA);
;             PG8_WAIT_V(8); PG8_WAIT_L(0); PG8_BAR; PG8_MMA(0, 0, At, B0); PG8_MMA(0, 1, At, B1); PG8_BAR; PG8_SCHED;
;             PG8_LDA(At, 0, 1); PG8_STAGE(PG8_SB(0, 0), b2, voffB); PG8_STAGE(PG8_SB(0, 1), b2 + hstep, voffB); PG8_STAGE(PG8_SA(0, 0), a2, voffA);
;             PG8_WAIT_V(8); PG8_WAIT_L(0); PG8_BAR; PG8_MMA(1, 0, At, B0); PG8_MMA(1, 1, At, B1); PG8_BAR; PG8_SCHED;
.LBB0_867:
	s_add_u32 s34, s44, 0x100
	s_addc_u32 s35, s45, 0
	s_mov_b32 s59, -2
	s_waitcnt lgkmcnt(0)
.Lpeel_p5:
	s_add_u32 s42, s20, 0x100
	s_addc_u32 s43, s21, 0
	s_add_i32 s30, 0, 0x10000
	s_cmp_eq_u32 s59, 40
	s_cselect_b32 s47, s11, s43
	s_cselect_b32 s46, s10, s42
	s_cselect_b32 s45, s15, s35
	s_cselect_b32 s44, s14, s34
	s_add_i32 s31, 0, 0x14000
	v_add_u32_e32 v134, s30, v191
	v_add_u32_e32 v168, s31, v191
	ds_read_b128 v[114:117], v134
	ds_read_b128 v[126:129], v134 offset:1024
	ds_read_b128 v[130:133], v134 offset:2048
	ds_read_b128 v[134:137], v134 offset:3072
	ds_read_b128 v[146:149], v168
	ds_read_b128 v[150:153], v168 offset:1024
	ds_read_b128 v[154:157], v168 offset:2048
	ds_read_b128 v[168:171], v168 offset:3072
	v_lshl_add_u64 v[188:189], s[20:21], 0, v[164:165]
	s_add_i32 m0, s48, 0xc000
	ds_read_b128 v[172:175], v202
	ds_read_b128 v[176:179], v202 offset:1024
	ds_read_b128 v[180:183], v202 offset:2048
	ds_read_b128 v[184:187], v202 offset:3072
	ds_read_b128 v[198:201], v202 offset:4096
	ds_read_b128 v[204:207], v202 offset:5120
	ds_read_b128 v[208:211], v202 offset:6144
	ds_read_b128 v[222:225], v202 offset:7168
	global_load_lds_dwordx4 v[188:189], off
	v_lshl_add_u64 v[188:189], s[20:21], 0, v[166:167]
	s_add_i32 m0, s48, 0xe000
	s_nop 0
	global_load_lds_dwordx4 v[188:189], off
	s_waitcnt vmcnt(8)
	s_waitcnt lgkmcnt(0)
	s_barrier
	s_setprio 1
	s_waitcnt lgkmcnt(0)
	v_mfma_f32_16x16x32_bf16 v[142:145], v[114:117], v[172:175], 0
	v_mfma_f32_16x16x32_bf16 v[138:141], v[130:133], v[172:175], 0
	v_mfma_f32_16x16x32_bf16 v[110:113], v[114:117], v[180:183], 0
	v_mfma_f32_16x16x32_bf16 v[106:109], v[130:133], v[180:183], 0
	v_mfma_f32_16x16x32_bf16 v[94:97], v[114:117], v[198:201], 0
	v_mfma_f32_16x16x32_bf16 v[90:93], v[130:133], v[198:201], 0
	v_mfma_f32_16x16x32_bf16 v[78:81], v[114:117], v[208:211], 0
	v_mfma_f32_16x16x32_bf16 v[74:77], v[130:133], v[208:211], 0
	v_mfma_f32_16x16x32_bf16 v[142:145], v[126:129], v[176:179], v[142:145]
	v_mfma_f32_16x16x32_bf16 v[138:141], v[134:137], v[176:179], v[138:141]
	v_mfma_f32_16x16x32_bf16 v[110:113], v[126:129], v[184:187], v[110:113]
	v_mfma_f32_16x16x32_bf16 v[106:109], v[134:137], v[184:187], v[106:109]
	v_mfma_f32_16x16x32_bf16 v[94:97], v[126:129], v[204:207], v[94:97]
	v_mfma_f32_16x16x32_bf16 v[90:93], v[134:137], v[204:207], v[90:93]
	v_mfma_f32_16x16x32_bf16 v[78:81], v[126:129], v[222:225], v[78:81]
	v_mfma_f32_16x16x32_bf16 v[74:77], v[134:137], v[222:225], v[74:77]
	s_setprio 0
	s_setprio 1
	v_mfma_f32_16x16x32_bf16 v[122:125], v[146:149], v[172:175], 0
	v_mfma_f32_16x16x32_bf16 v[118:121], v[154:157], v[172:175], 0
	v_mfma_f32_16x16x32_bf16 v[102:105], v[146:149], v[180:183], 0
	v_mfma_f32_16x16x32_bf16 v[98:101], v[154:157], v[180:183], 0
	v_mfma_f32_16x16x32_bf16 v[86:89], v[146:149], v[198:201], 0
	v_mfma_f32_16x16x32_bf16 v[82:85], v[154:157], v[198:201], 0
	v_mfma_f32_16x16x32_bf16 v[70:73], v[146:149], v[208:211], 0
	v_mfma_f32_16x16x32_bf16 v[66:69], v[154:157], v[208:211], 0
	v_mfma_f32_16x16x32_bf16 v[122:125], v[150:153], v[176:179], v[122:125]
	v_mfma_f32_16x16x32_bf16 v[118:121], v[168:171], v[176:179], v[118:121]
	v_mfma_f32_16x16x32_bf16 v[102:105], v[150:153], v[184:187], v[102:105]
	v_mfma_f32_16x16x32_bf16 v[98:101], v[168:171], v[184:187], v[98:101]
	v_mfma_f32_16x16x32_bf16 v[86:89], v[150:153], v[204:207], v[86:89]
	v_mfma_f32_16x16x32_bf16 v[82:85], v[168:171], v[204:207], v[82:85]
	v_mfma_f32_16x16x32_bf16 v[70:73], v[150:153], v[222:225], v[70:73]
	v_mfma_f32_16x16x32_bf16 v[66:69], v[168:171], v[222:225], v[66:69]
	s_setprio 0
	s_barrier
	s_add_i32 s20, s30, s33
	v_lshl_add_u64 v[188:189], s[44:45], 0, v[0:1]
	s_mov_b32 m0, s20
	ds_read_b128 v[172:175], v202 offset:16384
	ds_read_b128 v[176:179], v202 offset:17408
	ds_read_b128 v[180:183], v202 offset:18432
	ds_read_b128 v[184:187], v202 offset:19456
	ds_read_b128 v[198:201], v202 offset:20480
	ds_read_b128 v[204:207], v202 offset:21504
	ds_read_b128 v[208:211], v202 offset:22528
	ds_read_b128 v[222:225], v202 offset:23552
	global_load_lds_dwordx4 v[188:189], off
	s_add_i32 m0, s20, 0x2000
	s_add_u32 s20, s44, 0xb0000
	v_lshl_add_u64 v[226:227], s[44:45], 0, v[158:159]
	s_addc_u32 s21, s45, 0
	s_add_i32 s30, s31, s33
	global_load_lds_dwordx4 v[226:227], off
	v_lshl_add_u64 v[228:229], s[20:21], 0, v[0:1]
	s_mov_b32 m0, s30
	v_lshl_add_u64 v[230:231], s[46:47], 0, v[160:161]
	global_load_lds_dwordx4 v[228:229], off
	v_lshl_add_u64 v[228:229], s[20:21], 0, v[158:159]
	s_add_i32 m0, s30, 0x2000
	s_nop 0
	global_load_lds_dwordx4 v[228:229], off
	v_lshl_add_u64 v[228:229], s[46:47], 0, v[162:163]
	s_mov_b32 m0, s48
	s_nop 0
	global_load_lds_dwordx4 v[228:229], off
	s_mov_b32 m0, s49
	s_nop 0
	global_load_lds_dwordx4 v[230:231], off
	s_waitcnt vmcnt(8)
	s_waitcnt lgkmcnt(0)
	s_barrier
; #define PG8_STAGE(bufoff, gbase, voff) do { _Pragma("unroll") for (int _i = 0; _i < 2; ++_i) \
;         __builtin_amdgcn_global_load_lds((const unsigned*)((const char*)(gbase) + (voff)[_i]), (PG8_LAS unsigned*)(lds + (bufoff) + ldsw + _i * 8192), 16, 0, 0); } while (0)
; #define PG8_LDA(dst, b, h) do { _Pragma("unroll") for (int m = 0; m < 4; ++m) _Pragma("unroll") for (int k = 0; k < 2; ++k) dst[m][k] = *(const PG8_LAS bf16x8*)(lds + PG8_SA(b, h) + aoff + m * 2048 + k * 1024); } while (0)
; #define PG8_LDB(dst, b, h) do { _Pragma("unroll") for (int n = 0; n < 2; ++n) _Pragma("unroll") for (int k = 0; k < 2; ++k) dst[n][k] = *(const PG8_LAS bf16x8*)(lds + PG8_SB(b, h) + boff + n * 2048 + k * 1024); } while (0)
; #define PG8_MMA(ai, bj, At, Bt) do { __builtin_amdgcn_s_setprio(1); _Pragma("unroll") for (int m = 0; m < 4; ++m) _Pragma("unroll") for (int n = 0; n < 2; ++n) _Pragma("unroll") for (int k = 0; k < 2; ++k) \
;         acc[ai][bj][m][n] = __builtin_amdgcn_mfma_f32_16x16x32_bf16(Bt[n][k], At[m][k], acc[ai][bj][m][n], 0, 0, 0); __builtin_amdgcn_s_setprio(0); } while (0)
; #define PG8_WAIT_V(n) asm volatile("s_waitcnt vmcnt(" #n ")" ::: "memory")
; #define PG8_WAIT_L(n) asm volatile("s_waitcnt lgkmcnt(" #n ")" ::: "memory")
; #define PG8_BAR __builtin_amdgcn_s_barrier()
; #define PG8_SCHED __builtin_amdgcn_sched_barrier(0)
; template <class Epi, class Sched, bool ALIGN_EPI = false, bool SP2 = false>
; __device__ __forceinline__ void gemm_phase(PG8_LAS unsigned char* lds, const Gemm g, const Sched& S, const Epi& E) {
;     ...
;             PG8_WAIT_V(8); PG8_WAIT_L(0); PG8_BAR; PG8_MMA(1, 0, At, B0); PG8_MMA(1, 1, At, B1); PG8_BAR; PG8_SCHED;
;             PG8_LDB(B0, 1, 0); PG8_LDB(B1, 1, 1); PG8_SCHED; PG8_LDA(At, 1, 0); PG8_STAGE(PG8_SA(0, 1), a2 + hstep, voffA);
;             PG8_WAIT_V(8); PG8_WAIT_L(0); PG8_BAR; PG8_MMA(0, 0, At, B0); PG8_MMA(0, 1, At, B1); PG8_BAR; PG8_SCHED;
;             PG8_LDA(At, 1, 1); PG8_STAGE(PG8_SB(1, 0), b3, voffB); PG8_STAGE(PG8_SB(1, 1), b3 + hstep, voffB); PG8_STAGE(PG8_SA(1, 0), a3, voffA);
	s_setprio 1
	s_waitcnt lgkmcnt(0)
	v_mfma_f32_16x16x32_bf16 v[62:65], v[114:117], v[172:175], 0
	v_mfma_f32_16x16x32_bf16 v[58:61], v[130:133], v[172:175], 0
	v_mfma_f32_16x16x32_bf16 v[46:49], v[114:117], v[180:183], 0
	v_mfma_f32_16x16x32_bf16 v[42:45], v[130:133], v[180:183], 0
	v_mfma_f32_16x16x32_bf16 v[30:33], v[114:117], v[198:201], 0
	v_mfma_f32_16x16x32_bf16 v[26:29], v[130:133], v[198:201], 0
	v_mfma_f32_16x16x32_bf16 v[14:17], v[114:117], v[208:211], 0
	v_mfma_f32_16x16x32_bf16 v[10:13], v[130:133], v[208:211], 0
	v_mfma_f32_16x16x32_bf16 v[62:65], v[126:129], v[176:179], v[62:65]
	v_mfma_f32_16x16x32_bf16 v[58:61], v[134:137], v[176:179], v[58:61]
	v_mfma_f32_16x16x32_bf16 v[46:49], v[126:129], v[184:187], v[46:49]
	v_mfma_f32_16x16x32_bf16 v[42:45], v[134:137], v[184:187], v[42:45]
	v_mfma_f32_16x16x32_bf16 v[30:33], v[126:129], v[204:207], v[30:33]
	v_mfma_f32_16x16x32_bf16 v[26:29], v[134:137], v[204:207], v[26:29]
	v_mfma_f32_16x16x32_bf16 v[14:17], v[126:129], v[222:225], v[14:17]
	v_mfma_f32_16x16x32_bf16 v[10:13], v[134:137], v[222:225], v[10:13]
	s_setprio 0
	s_setprio 1
	v_mfma_f32_16x16x32_bf16 v[54:57], v[146:149], v[172:175], 0
	v_mfma_f32_16x16x32_bf16 v[50:53], v[154:157], v[172:175], 0
	v_mfma_f32_16x16x32_bf16 v[38:41], v[146:149], v[180:183], 0
	v_mfma_f32_16x16x32_bf16 v[34:37], v[154:157], v[180:183], 0
	v_mfma_f32_16x16x32_bf16 v[22:25], v[146:149], v[198:201], 0
	v_mfma_f32_16x16x32_bf16 v[18:21], v[154:157], v[198:201], 0
	v_mfma_f32_16x16x32_bf16 v[6:9], v[146:149], v[208:211], 0
	v_mfma_f32_16x16x32_bf16 v[2:5], v[154:157], v[208:211], 0
	v_mfma_f32_16x16x32_bf16 v[54:57], v[150:153], v[176:179], v[54:57]
	v_mfma_f32_16x16x32_bf16 v[50:53], v[168:171], v[176:179], v[50:53]
	v_mfma_f32_16x16x32_bf16 v[38:41], v[150:153], v[184:187], v[38:41]
	v_mfma_f32_16x16x32_bf16 v[34:37], v[168:171], v[184:187], v[34:37]
	v_mfma_f32_16x16x32_bf16 v[22:25], v[150:153], v[204:207], v[22:25]
	v_mfma_f32_16x16x32_bf16 v[18:21], v[168:171], v[204:207], v[18:21]
	v_mfma_f32_16x16x32_bf16 v[6:9], v[150:153], v[222:225], v[6:9]
	v_mfma_f32_16x16x32_bf16 v[2:5], v[168:171], v[222:225], v[2:5]
	s_setprio 0
	s_barrier
	s_add_i32 s30, 0, 0x18000
	s_add_i32 s31, 0, 0x1c000
	v_add_u32_e32 v134, s30, v191
	v_add_u32_e32 v168, s31, v191
	ds_read_b128 v[114:117], v134
	ds_read_b128 v[126:129], v134 offset:1024
	ds_read_b128 v[130:133], v134 offset:2048
	ds_read_b128 v[134:137], v134 offset:3072
	ds_read_b128 v[146:149], v168
	ds_read_b128 v[150:153], v168 offset:1024
	ds_read_b128 v[154:157], v168 offset:2048
	ds_read_b128 v[168:171], v168 offset:3072
	s_add_u32 s20, s46, 0xb0000
	s_addc_u32 s21, s47, 0
	s_mov_b32 m0, s50
	v_lshl_add_u64 v[232:233], s[20:21], 0, v[162:163]
	ds_read_b128 v[172:175], v202 offset:32768
	ds_read_b128 v[176:179], v202 offset:33792
	ds_read_b128 v[180:183], v202 offset:34816
	ds_read_b128 v[184:187], v202 offset:35840
	ds_read_b128 v[198:201], v202 offset:36864
	ds_read_b128 v[204:207], v202 offset:37888
	ds_read_b128 v[208:211], v202 offset:38912
	ds_read_b128 v[222:225], v202 offset:39936
	global_load_lds_dwordx4 v[232:233], off
	v_lshl_add_u64 v[232:233], s[20:21], 0, v[160:161]
	s_mov_b32 m0, s51
	s_nop 0
	global_load_lds_dwordx4 v[232:233], off
	s_waitcnt vmcnt(8)
	s_waitcnt lgkmcnt(0)
	s_barrier
	s_setprio 1
	s_waitcnt lgkmcnt(0)
	v_mfma_f32_16x16x32_bf16 v[142:145], v[114:117], v[172:175], v[142:145]
	v_mfma_f32_16x16x32_bf16 v[138:141], v[130:133], v[172:175], v[138:141]
	v_mfma_f32_16x16x32_bf16 v[110:113], v[114:117], v[180:183], v[110:113]
	v_mfma_f32_16x16x32_bf16 v[106:109], v[130:133], v[180:183], v[106:109]
	v_mfma_f32_16x16x32_bf16 v[94:97], v[114:117], v[198:201], v[94:97]
	v_mfma_f32_16x16x32_bf16 v[90:93], v[130:133], v[198:201], v[90:93]
	v_mfma_f32_16x16x32_bf16 v[78:81], v[114:117], v[208:211], v[78:81]
	v_mfma_f32_16x16x32_bf16 v[74:77], v[130:133], v[208:211], v[74:77]
	v_mfma_f32_16x16x32_bf16 v[142:145], v[126:129], v[176:179], v[142:145]
	v_mfma_f32_16x16x32_bf16 v[138:141], v[134:137], v[176:179], v[138:141]
	v_mfma_f32_16x16x32_bf16 v[110:113], v[126:129], v[184:187], v[110:113]
	v_mfma_f32_16x16x32_bf16 v[106:109], v[134:137], v[184:187], v[106:109]
	v_mfma_f32_16x16x32_bf16 v[94:97], v[126:129], v[204:207], v[94:97]
	v_mfma_f32_16x16x32_bf16 v[90:93], v[134:137], v[204:207], v[90:93]
	v_mfma_f32_16x16x32_bf16 v[78:81], v[126:129], v[222:225], v[78:81]
	v_mfma_f32_16x16x32_bf16 v[74:77], v[134:137], v[222:225], v[74:77]
	s_setprio 0
	s_setprio 1
	v_mfma_f32_16x16x32_bf16 v[122:125], v[146:149], v[172:175], v[122:125]
	v_mfma_f32_16x16x32_bf16 v[118:121], v[154:157], v[172:175], v[118:121]
	v_mfma_f32_16x16x32_bf16 v[102:105], v[146:149], v[180:183], v[102:105]
	v_mfma_f32_16x16x32_bf16 v[98:101], v[154:157], v[180:183], v[98:101]
	v_mfma_f32_16x16x32_bf16 v[86:89], v[146:149], v[198:201], v[86:89]
	v_mfma_f32_16x16x32_bf16 v[82:85], v[154:157], v[198:201], v[82:85]
	v_mfma_f32_16x16x32_bf16 v[70:73], v[146:149], v[208:211], v[70:73]
	v_mfma_f32_16x16x32_bf16 v[66:69], v[154:157], v[208:211], v[66:69]
	v_mfma_f32_16x16x32_bf16 v[122:125], v[150:153], v[176:179], v[122:125]
	v_mfma_f32_16x16x32_bf16 v[118:121], v[168:171], v[176:179], v[118:121]
	v_mfma_f32_16x16x32_bf16 v[102:105], v[150:153], v[184:187], v[102:105]
	v_mfma_f32_16x16x32_bf16 v[98:101], v[168:171], v[184:187], v[98:101]
	v_mfma_f32_16x16x32_bf16 v[86:89], v[150:153], v[204:207], v[86:89]
	v_mfma_f32_16x16x32_bf16 v[82:85], v[168:171], v[204:207], v[82:85]
	v_mfma_f32_16x16x32_bf16 v[70:73], v[150:153], v[222:225], v[70:73]
	v_mfma_f32_16x16x32_bf16 v[66:69], v[168:171], v[222:225], v[66:69]
	s_setprio 0
	s_barrier
; #define PG8_STAGE(bufoff, gbase, voff) do { _Pragma("unroll") for (int _i = 0; _i < 2; ++_i) \
;         __builtin_amdgcn_global_load_lds((const unsigned*)((const char*)(gbase) + (voff)[_i]), (PG8_LAS unsigned*)(lds + (bufoff) + ldsw + _i * 8192), 16, 0, 0); } while (0)
; #define PG8_LDA(dst, b, h) do { _Pragma("unroll") for (int m = 0; m < 4; ++m) _Pragma("unroll") for (int k = 0; k < 2; ++k) dst[m][k] = *(const PG8_LAS bf16x8*)(lds + PG8_SA(b, h) + aoff + m * 2048 + k * 1024); } while (0)
; #define PG8_MMA(ai, bj, At, Bt) do { __builtin_amdgcn_s_setprio(1); _Pragma("unroll") for (int m = 0; m < 4; ++m) _Pragma("unroll") for (int n = 0; n < 2; ++n) _Pragma("unroll") for (int k = 0; k < 2; ++k) \
;         acc[ai][bj][m][n] = __builtin_amdgcn_mfma_f32_16x16x32_bf16(Bt[n][k], At[m][k], acc[ai][bj][m][n], 0, 0, 0); __builtin_amdgcn_s_setprio(0); } while (0)
; #define PG8_WAIT_V(n) asm volatile("s_waitcnt vmcnt(" #n ")" ::: "memory")
; #define PG8_WAIT_L(n) asm volatile("s_waitcnt lgkmcnt(" #n ")" ::: "memory")
; #define PG8_BAR __builtin_amdgcn_s_barrier()
; #define PG8_SCHED __builtin_amdgcn_sched_barrier(0)
; template <class Epi, class Sched, bool ALIGN_EPI = false, bool SP2 = false>
; __device__ __forceinline__ void gemm_phase(PG8_LAS unsigned char* lds, const Gemm g, const Sched& S, const Epi& E) {
;     ...
;             PG8_LDA(At, 1, 1); PG8_STAGE(PG8_SB(1, 0), b3, voffB); PG8_STAGE(PG8_SB(1, 1), b3 + hstep, voffB); PG8_STAGE(PG8_SA(1, 0), a3, voffA);
;             PG8_WAIT_V(8); PG8_WAIT_L(0); PG8_BAR; PG8_MMA(1, 0, At, B0); PG8_MMA(1, 1, At, B1); PG8_BAR; PG8_SCHED;
	s_add_i32 s20, s30, s33
	v_lshl_add_u64 v[188:189], v[188:189], 0, s[0:1]
	s_mov_b32 m0, s20
	ds_read_b128 v[172:175], v202 offset:49152
	ds_read_b128 v[176:179], v202 offset:50176
	ds_read_b128 v[180:183], v202 offset:51200
	ds_read_b128 v[184:187], v202 offset:52224
	ds_read_b128 v[198:201], v202 offset:53248
	ds_read_b128 v[204:207], v202 offset:54272
	ds_read_b128 v[208:211], v202 offset:55296
	ds_read_b128 v[222:225], v202 offset:56320
	global_load_lds_dwordx4 v[188:189], off
	s_add_i32 m0, s20, 0x2000
	s_add_u32 s20, s44, 0xb0080
	v_lshl_add_u64 v[188:189], v[226:227], 0, s[0:1]
	s_addc_u32 s21, s45, 0
	s_add_i32 s30, s31, s33
	global_load_lds_dwordx4 v[188:189], off
	v_lshl_add_u64 v[188:189], s[20:21], 0, v[0:1]
	s_mov_b32 m0, s30
	s_nop 0
	global_load_lds_dwordx4 v[188:189], off
	v_lshl_add_u64 v[188:189], s[20:21], 0, v[158:159]
	s_add_i32 m0, s30, 0x2000
	s_nop 0
	global_load_lds_dwordx4 v[188:189], off
	v_lshl_add_u64 v[188:189], v[228:229], 0, s[0:1]
	s_mov_b32 m0, s54
	s_nop 0
	global_load_lds_dwordx4 v[188:189], off
	v_lshl_add_u64 v[188:189], v[230:231], 0, s[0:1]
	s_mov_b32 m0, s55
	s_nop 0
	global_load_lds_dwordx4 v[188:189], off
	s_waitcnt vmcnt(8)
	s_waitcnt lgkmcnt(0)
	s_barrier
	s_setprio 1
	s_waitcnt lgkmcnt(0)
	v_mfma_f32_16x16x32_bf16 v[62:65], v[114:117], v[172:175], v[62:65]
	v_mfma_f32_16x16x32_bf16 v[58:61], v[130:133], v[172:175], v[58:61]
	v_mfma_f32_16x16x32_bf16 v[46:49], v[114:117], v[180:183], v[46:49]
	v_mfma_f32_16x16x32_bf16 v[42:45], v[130:133], v[180:183], v[42:45]
	v_mfma_f32_16x16x32_bf16 v[30:33], v[114:117], v[198:201], v[30:33]
	v_mfma_f32_16x16x32_bf16 v[26:29], v[130:133], v[198:201], v[26:29]
	v_mfma_f32_16x16x32_bf16 v[14:17], v[114:117], v[208:211], v[14:17]
	v_mfma_f32_16x16x32_bf16 v[10:13], v[130:133], v[208:211], v[10:13]
	v_mfma_f32_16x16x32_bf16 v[62:65], v[126:129], v[176:179], v[62:65]
	v_mfma_f32_16x16x32_bf16 v[58:61], v[134:137], v[176:179], v[58:61]
	v_mfma_f32_16x16x32_bf16 v[46:49], v[126:129], v[184:187], v[46:49]
	v_mfma_f32_16x16x32_bf16 v[42:45], v[134:137], v[184:187], v[42:45]
	v_mfma_f32_16x16x32_bf16 v[30:33], v[126:129], v[204:207], v[30:33]
	v_mfma_f32_16x16x32_bf16 v[26:29], v[134:137], v[204:207], v[26:29]
	v_mfma_f32_16x16x32_bf16 v[14:17], v[126:129], v[222:225], v[14:17]
	v_mfma_f32_16x16x32_bf16 v[10:13], v[134:137], v[222:225], v[10:13]
	s_setprio 0
	s_setprio 1
	v_mfma_f32_16x16x32_bf16 v[54:57], v[146:149], v[172:175], v[54:57]
	v_mfma_f32_16x16x32_bf16 v[50:53], v[154:157], v[172:175], v[50:53]
	v_mfma_f32_16x16x32_bf16 v[38:41], v[146:149], v[180:183], v[38:41]
	v_mfma_f32_16x16x32_bf16 v[34:37], v[154:157], v[180:183], v[34:37]
	v_mfma_f32_16x16x32_bf16 v[22:25], v[146:149], v[198:201], v[22:25]
	v_mfma_f32_16x16x32_bf16 v[18:21], v[154:157], v[198:201], v[18:21]
	v_mfma_f32_16x16x32_bf16 v[6:9], v[146:149], v[208:211], v[6:9]
	v_mfma_f32_16x16x32_bf16 v[2:5], v[154:157], v[208:211], v[2:5]
	v_mfma_f32_16x16x32_bf16 v[54:57], v[150:153], v[176:179], v[54:57]
	v_mfma_f32_16x16x32_bf16 v[50:53], v[168:171], v[176:179], v[50:53]
	v_mfma_f32_16x16x32_bf16 v[38:41], v[150:153], v[184:187], v[38:41]
	v_mfma_f32_16x16x32_bf16 v[34:37], v[168:171], v[184:187], v[34:37]
	v_mfma_f32_16x16x32_bf16 v[22:25], v[150:153], v[204:207], v[22:25]
	v_mfma_f32_16x16x32_bf16 v[18:21], v[168:171], v[204:207], v[18:21]
	v_mfma_f32_16x16x32_bf16 v[6:9], v[150:153], v[222:225], v[6:9]
	v_mfma_f32_16x16x32_bf16 v[2:5], v[168:171], v[222:225], v[2:5]
	s_setprio 0
	s_barrier
	s_add_i32 s59, s59, 2
	s_add_u32 s34, s34, 0x100
	s_addc_u32 s35, s35, 0
	s_cmp_gt_u32 s59, 41
	s_mov_b64 s[20:21], s[42:43]
	s_cbranch_scc0 .LBB0_868
	s_branch .Lpeel_exit_p5
